# P4: exp/cvt pipelined under PV MFMAs + bias VALU under QK MFMAs; P1 epilogue: store-draining vmcnt waits removed, rotary table loads hoisted with counted waits
# speedup vs baseline: 1.0088x; 1.0039x over previous
; __device__ __forceinline__ unsigned cvt_pk_bf16(float lo, float hi) { unsigned r; asm volatile("v_cvt_pk_bf16_f32 %0, %1, %2" : "=v"(r) : "v"(lo), "v"(hi)); return r; }
; __device__ __forceinline__ float sigmoidf_(float v) { return __builtin_amdgcn_rcpf(1.0f + __builtin_amdgcn_exp2f(-1.4426950408889634f * v)); }
;     __device__ __forceinline__ void operator()(const f32x4 (&acc)[2][2][4][2], const Unit& u, int wr, int wc, int fr, int fq) const {
;         const int row0 = u.pm * BM + wr * 64 + fr; const int col0 = u.pn * BM + wc * 32 + 8 * fq;
;         const bool rope = (u.pn >= 4 && u.pn < 8) || u.pn == 10 || u.pn == 11; const float sc = (u.pn == 4 || u.pn == 5) ? qscale : 1.0f;
;         const bool kv = u.pn >= 6 && u.pn < 10;
;         const int fo = 16 * (wc & 1) + 4 * fq;
;         if (u.pn < 4) {
; #pragma unroll
;             for (int ai = 0; ai < 2; ++ai)
; #pragma unroll
;                 for (int m = 0; m < 4; ++m) { const int row = row0 + ai * HALF + m * 16; const f32x4 a0 = acc[ai][0][m][0], a1 = acc[ai][0][m][1], g0 = acc[ai][1][m][0], g1 = acc[ai][1][m][1];
;                     u32x4 w; w.x = cvt_pk_bf16(a0[0] * sigmoidf_(g0[0]), a0[1] * sigmoidf_(g0[1])); w.y = cvt_pk_bf16(a0[2] * sigmoidf_(g0[2]), a0[3] * sigmoidf_(g0[3]));
;                     w.z = cvt_pk_bf16(a1[0] * sigmoidf_(g1[0]), a1[1] * sigmoidf_(g1[1])); w.w = cvt_pk_bf16(a1[2] * sigmoidf_(g1[2]), a1[3] * sigmoidf_(g1[3]));
;                     *(u32x4*)(O + (size_t)row * ldc + u.pn * 128 + wc * 32 + 8 * fq) = w; }
;             return; }
; #pragma unroll
;         for (int ai = 0; ai < 2; ++ai)
; #pragma unroll
;             for (int m = 0; m < 4; ++m) { const int row = row0 + ai * HALF + m * 16; bf16_t* rowp = O + (size_t)row * ldc + col0;
;                 f32x4 cs = (f32x4){1.f, 1.f, 1.f, 1.f}, sn = (f32x4){0.f, 0.f, 0.f, 0.f};
;                 if (rope) { const float* tp = tab + (size_t)(row & 4095) * 32 + fo; cs = *(const f32x4*)tp; sn = *(const f32x4*)(tp + 4096 * 32); }
.LBB0_194:
	s_lshl_b32 s41, s4, 8
	s_add_i32 s41, s41, s53
	v_or_b32_e32 v184, s41, v176
	s_cmp_lt_i32 s46, 4
	s_mov_b64 s[4:5], -1
	s_cbranch_scc1 .LBB0_197
	s_cmp_gt_u32 s46, 7
	s_cselect_b64 s[4:5], -1, 0
	s_cmp_lt_u32 s46, 8
	s_cselect_b64 s[6:7], -1, 0
	s_and_b32 s8, s46, 0x7ffffffe
	s_cmp_eq_u32 s8, 10
	s_cselect_b64 s[8:9], -1, 0
	s_or_b64 s[6:7], s[6:7], s[8:9]
	s_and_b64 vcc, exec, s[6:7]
	s_cbranch_vccz .LBB0_199
	v_lshlrev_b32_e32 v128, 7, v184
	v_and_b32_e32 v148, 0x7e780, v128
	v_lshl_add_u64 v[128:129], v[150:151], 0, v[148:149]
	v_add_co_u32_e32 v132, vcc, 0x80000, v128
	s_nop 1
	v_addc_co_u32_e32 v133, vcc, 0, v129, vcc
	global_load_dwordx4 v[194:197], v[128:129], off
	s_nop 0
	global_load_dwordx4 v[198:201], v[132:133], off
	v_or_b32_e32 v128, 16, v184
	v_lshlrev_b32_e32 v128, 7, v128
	v_and_b32_e32 v148, 0x7ef80, v128
	v_lshl_add_u64 v[128:129], v[150:151], 0, v[148:149]
	v_add_co_u32_e32 v132, vcc, 0x80000, v128
	s_nop 1
	v_addc_co_u32_e32 v133, vcc, 0, v129, vcc
	global_load_dwordx4 v[202:205], v[128:129], off
	s_nop 0
	global_load_dwordx4 v[206:209], v[132:133], off
	v_or_b32_e32 v128, 32, v184
	v_lshlrev_b32_e32 v128, 7, v128
	v_and_b32_e32 v148, 0x7f780, v128
	v_lshl_add_u64 v[128:129], v[150:151], 0, v[148:149]
	v_add_co_u32_e32 v132, vcc, 0x80000, v128
	s_nop 1
	v_addc_co_u32_e32 v133, vcc, 0, v129, vcc
	global_load_dwordx4 v[210:213], v[128:129], off
	s_nop 0
	global_load_dwordx4 v[214:217], v[132:133], off
	v_or_b32_e32 v128, 48, v184
	v_lshlrev_b32_e32 v128, 7, v128
	v_and_b32_e32 v148, 0x7ff80, v128
	v_lshl_add_u64 v[128:129], v[150:151], 0, v[148:149]
	v_add_co_u32_e32 v132, vcc, 0x80000, v128
	s_nop 1
	v_addc_co_u32_e32 v133, vcc, 0, v129, vcc
	global_load_dwordx4 v[222:225], v[128:129], off
	s_nop 0
	global_load_dwordx4 v[226:229], v[132:133], off
	v_add_u32_e32 v128, 0x80, v184
	v_lshlrev_b32_e32 v128, 7, v128
	v_and_b32_e32 v148, 0x7e780, v128
	v_lshl_add_u64 v[128:129], v[150:151], 0, v[148:149]
	v_add_co_u32_e32 v132, vcc, 0x80000, v128
	s_nop 1
	v_addc_co_u32_e32 v133, vcc, 0, v129, vcc
	global_load_dwordx4 v[230:233], v[128:129], off
	s_nop 0
	global_load_dwordx4 v[234:237], v[132:133], off
	s_branch .LBB0_200

; __device__ __forceinline__ unsigned cvt_pk_bf16(float lo, float hi) { unsigned r; asm volatile("v_cvt_pk_bf16_f32 %0, %1, %2" : "=v"(r) : "v"(lo), "v"(hi)); return r; }
;     __device__ __forceinline__ void operator()(const f32x4 (&acc)[2][2][4][2], const Unit& u, int wr, int wc, int fr, int fq) const {
;     ...
;                 for (int bj = 0; bj < 2; ++bj) { f32x4 v0 = acc[ai][bj][m][0], v1 = acc[ai][bj][m][1];
;                     if (rope) {
; #pragma unroll
;                         for (int i = 0; i < 4; ++i) { const float a = v0[i], b = v1[i]; v0[i] = (a * cs[i] - b * sn[i]) * sc; v1[i] = (b * cs[i] + a * sn[i]) * sc; } }
;                     u32x4 w; w.x = cvt_pk_bf16(v0[0], v0[1]); w.y = cvt_pk_bf16(v0[2], v0[3]); w.z = cvt_pk_bf16(v1[0], v1[1]); w.w = cvt_pk_bf16(v1[2], v1[3]);
.LBB0_200:
	s_and_b32 s8, s46, -2
	s_cmp_eq_u32 s8, 4
	s_cselect_b64 vcc, -1, 0
	v_cndmask_b32_e64 v136, 0, 1, s[6:7]
	v_cndmask_b32_e32 v166, 1.0, v183, vcc
	v_cmp_ne_u32_e64 s[8:9], 1, v136
	s_andn2_b64 vcc, exec, s[6:7]
	v_mov_b32_e32 v136, v124
	v_mov_b32_e32 v137, v125
	v_mov_b32_e32 v172, v126
	v_mov_b32_e32 v173, v127
	v_mov_b32_e32 v138, v116
	v_mov_b32_e32 v139, v117
	v_mov_b32_e32 v174, v118
	v_mov_b32_e32 v175, v119
	s_cbranch_vccnz .LBB0_202
	v_mov_b32_e32 v188, v127
	v_mov_b32_e32 v189, v119
	s_waitcnt vmcnt(8)
	v_mov_b32_e32 v172, v197
	v_mov_b32_e32 v173, v201
	v_pk_mul_f32 v[172:173], v[188:189], v[172:173]
	v_mul_f32_e32 v168, v126, v196
	v_mul_f32_e32 v170, v118, v200
	v_mov_b32_e32 v169, v172
	v_mov_b32_e32 v171, v173
	v_pk_add_f32 v[168:169], v[168:169], v[170:171] neg_lo:[0,1] neg_hi:[0,1]
	v_pk_mul_f32 v[136:137], v[116:117], v[198:199]
	v_pk_mul_f32 v[172:173], v[166:167], v[168:169] op_sel_hi:[0,1]
	v_mov_b32_e32 v168, v201
	v_mov_b32_e32 v169, v197
	v_pk_mul_f32 v[168:169], v[188:189], v[168:169]
	v_pk_mul_f32 v[138:139], v[116:117], v[194:195]
	v_mul_f32_e32 v174, v118, v196
	v_mul_f32_e32 v186, v126, v200
	v_mov_b32_e32 v187, v168
	v_mov_b32_e32 v175, v169
	v_pk_fma_f32 v[136:137], v[124:125], v[194:195], v[136:137] neg_lo:[0,0,1] neg_hi:[0,0,1]
	v_pk_fma_f32 v[138:139], v[124:125], v[198:199], v[138:139]
	v_pk_add_f32 v[168:169], v[186:187], v[174:175]
	v_pk_mul_f32 v[136:137], v[166:167], v[136:137] op_sel_hi:[0,1]
	v_pk_mul_f32 v[138:139], v[166:167], v[138:139] op_sel_hi:[0,1]
	v_pk_mul_f32 v[174:175], v[166:167], v[168:169] op_sel_hi:[0,1]

; __device__ __forceinline__ unsigned cvt_pk_bf16(float lo, float hi) { unsigned r; asm volatile("v_cvt_pk_bf16_f32 %0, %1, %2" : "=v"(r) : "v"(lo), "v"(hi)); return r; }
;     __device__ __forceinline__ void operator()(const f32x4 (&acc)[2][2][4][2], const Unit& u, int wr, int wc, int fr, int fq) const {
;     ...
;                 for (int bj = 0; bj < 2; ++bj) { f32x4 v0 = acc[ai][bj][m][0], v1 = acc[ai][bj][m][1];
;                     if (rope) {
; #pragma unroll
;                         for (int i = 0; i < 4; ++i) { const float a = v0[i], b = v1[i]; v0[i] = (a * cs[i] - b * sn[i]) * sc; v1[i] = (b * cs[i] + a * sn[i]) * sc; } }
;                     u32x4 w; w.x = cvt_pk_bf16(v0[0], v0[1]); w.y = cvt_pk_bf16(v0[2], v0[3]); w.z = cvt_pk_bf16(v1[0], v1[1]); w.w = cvt_pk_bf16(v1[2], v1[3]);
;                     if (kv) {
;                         const int cseg = (u.pn & 1) * 256 + bj * HALF + wc * 32 + 8 * fq; const unsigned hd = (unsigned)cseg >> 6, dl = ((unsigned)cseg & 63u) >> 3;
;                         const unsigned pos = (unsigned)row & 4095u, key = pos & 63u; const unsigned rb = ((unsigned)row >> 12) * 2097152u + hd * 262144u + (pos >> 6) * 4096u;
;                         if (u.pn < 8) *(u32x4*)(Kb + rb + dl * 512u + key * 8u) = w;
;                         else *(u32x4*)(Vb + rb + (dl >> 2) * 2048u + (key >> 4) * 512u + (key & 15u) * 32u + (dl & 3u) * 8u) = w;
;                     } else *(u32x4*)(rowp + bj * HALF) = w; } }
.LBB0_209:
	s_and_b64 vcc, exec, s[8:9]
	s_nop 0
	v_mov_b32_e32 v136, v120
	v_mov_b32_e32 v137, v121
	v_mov_b32_e32 v172, v122
	v_mov_b32_e32 v173, v123
	v_mov_b32_e32 v138, v112
	v_mov_b32_e32 v139, v113
	v_mov_b32_e32 v174, v114
	v_mov_b32_e32 v175, v115
	s_cbranch_vccnz .LBB0_211
	s_nop 0
	v_pk_mul_f32 v[136:137], v[112:113], v[198:199]
	v_mul_f32_e32 v186, v122, v200
	v_pk_fma_f32 v[136:137], v[120:121], v[194:195], v[136:137] neg_lo:[0,0,1] neg_hi:[0,0,1]
	v_pk_mul_f32 v[194:195], v[112:113], v[194:195]
	v_mov_b32_e32 v188, v123
	v_pk_fma_f32 v[194:195], v[120:121], v[198:199], v[194:195]
	v_mul_f32_e32 v198, v114, v200
	v_mov_b32_e32 v189, v115
	v_mov_b32_e32 v200, v197
	v_pk_mul_f32 v[172:173], v[188:189], v[200:201]
	v_pk_mul_f32 v[138:139], v[166:167], v[194:195] op_sel_hi:[0,1]
	v_mul_f32_e32 v194, v122, v196
	v_mov_b32_e32 v195, v172
	v_mov_b32_e32 v199, v173
	v_mul_f32_e32 v174, v114, v196
	v_pk_add_f32 v[194:195], v[194:195], v[198:199] neg_lo:[0,1] neg_hi:[0,1]
	v_mov_b32_e32 v196, v201
	v_pk_mul_f32 v[172:173], v[166:167], v[194:195] op_sel_hi:[0,1]
	v_pk_mul_f32 v[194:195], v[188:189], v[196:197]
	v_pk_mul_f32 v[136:137], v[166:167], v[136:137] op_sel_hi:[0,1]
	v_mov_b32_e32 v187, v194
	v_mov_b32_e32 v175, v195
	v_pk_add_f32 v[194:195], v[186:187], v[174:175]
	s_nop 0
	v_pk_mul_f32 v[174:175], v[166:167], v[194:195] op_sel_hi:[0,1]
.LBB0_211:
	s_nop 0
	v_cndmask_b32_e64 v132, 0, 1, s[48:49]
	v_cmp_ne_u32_e64 s[6:7], 1, v132
	s_andn2_b64 vcc, exec, s[48:49]
	s_mov_b64 s[48:49], -1
	v_cvt_pk_bf16_f32 v128, v136, v137
	v_cvt_pk_bf16_f32 v129, v172, v173
	v_cvt_pk_bf16_f32 v130, v138, v139
	v_cvt_pk_bf16_f32 v131, v174, v175
	s_cbranch_vccnz .LBB0_213
	s_mov_b64 s[48:49], 0
	global_store_dwordx4 v[170:171], v[128:131], off offset:256

;     __device__ __forceinline__ void operator()(const f32x4 (&acc)[2][2][4][2], const Unit& u, int wr, int wc, int fr, int fq) const {
;     ...
;             for (int m = 0; m < 4; ++m) { const int row = row0 + ai * HALF + m * 16; bf16_t* rowp = O + (size_t)row * ldc + col0;
;                 f32x4 cs = (f32x4){1.f, 1.f, 1.f, 1.f}, sn = (f32x4){0.f, 0.f, 0.f, 0.f};
;                 if (rope) { const float* tp = tab + (size_t)(row & 4095) * 32 + fo; cs = *(const f32x4*)tp; sn = *(const f32x4*)(tp + 4096 * 32); }
.LBB0_218:
	s_and_b64 vcc, exec, s[8:9]
	v_or_b32_e32 v170, 16, v184
	s_cbranch_vccnz .LBB0_220
	v_add_u32_e32 v128, 0x90, v184
	v_lshlrev_b32_e32 v128, 7, v128
	v_and_b32_e32 v148, 0x7ef80, v128
	v_lshl_add_u64 v[128:129], v[150:151], 0, v[148:149]
	v_add_co_u32_e32 v132, vcc, 0x80000, v128
	s_nop 1
	v_addc_co_u32_e32 v133, vcc, 0, v129, vcc
	global_load_dwordx4 v[112:115], v[128:129], off
	s_nop 0
	global_load_dwordx4 v[116:119], v[132:133], off
	v_add_u32_e32 v128, 0xa0, v184
	v_lshlrev_b32_e32 v128, 7, v128
	v_and_b32_e32 v148, 0x7f780, v128
	v_lshl_add_u64 v[128:129], v[150:151], 0, v[148:149]
	v_add_co_u32_e32 v132, vcc, 0x80000, v128
	s_nop 1
	v_addc_co_u32_e32 v133, vcc, 0, v129, vcc
	global_load_dwordx4 v[120:123], v[128:129], off
	s_nop 0
	global_load_dwordx4 v[124:127], v[132:133], off
	s_branch .LBB0_221

; __device__ __forceinline__ unsigned cvt_pk_bf16(float lo, float hi) { unsigned r; asm volatile("v_cvt_pk_bf16_f32 %0, %1, %2" : "=v"(r) : "v"(lo), "v"(hi)); return r; }
;     __device__ __forceinline__ void operator()(const f32x4 (&acc)[2][2][4][2], const Unit& u, int wr, int wc, int fr, int fq) const {
;     ...
;                 for (int bj = 0; bj < 2; ++bj) { f32x4 v0 = acc[ai][bj][m][0], v1 = acc[ai][bj][m][1];
;                     if (rope) {
; #pragma unroll
;                         for (int i = 0; i < 4; ++i) { const float a = v0[i], b = v1[i]; v0[i] = (a * cs[i] - b * sn[i]) * sc; v1[i] = (b * cs[i] + a * sn[i]) * sc; } }
;                     u32x4 w; w.x = cvt_pk_bf16(v0[0], v0[1]); w.y = cvt_pk_bf16(v0[2], v0[3]); w.z = cvt_pk_bf16(v1[0], v1[1]); w.w = cvt_pk_bf16(v1[2], v1[3]);
.LBB0_221:
	s_and_b64 vcc, exec, s[8:9]
	v_mov_b32_e32 v136, v108
	v_mov_b32_e32 v137, v109
	v_mov_b32_e32 v172, v110
	v_mov_b32_e32 v173, v111
	v_mov_b32_e32 v138, v100
	v_mov_b32_e32 v139, v101
	v_mov_b32_e32 v174, v102
	v_mov_b32_e32 v175, v103
	s_cbranch_vccnz .LBB0_223
	v_mov_b32_e32 v190, v111
	v_mov_b32_e32 v191, v103
	s_waitcnt vmcnt(12)
	v_mov_b32_e32 v192, v205
	s_nop 0
	v_mov_b32_e32 v193, v209
	v_pk_mul_f32 v[192:193], v[190:191], v[192:193]
	v_mul_f32_e32 v172, v110, v204
	v_mul_f32_e32 v174, v102, v208
	v_mov_b32_e32 v173, v192
	v_mov_b32_e32 v175, v193
	v_pk_add_f32 v[172:173], v[172:173], v[174:175] neg_lo:[0,1] neg_hi:[0,1]
	v_mov_b32_e32 v174, v209
	v_mov_b32_e32 v175, v205
	v_pk_mul_f32 v[174:175], v[190:191], v[174:175]
	v_pk_mul_f32 v[136:137], v[100:101], v[206:207]
	v_pk_mul_f32 v[138:139], v[100:101], v[202:203]
	v_mul_f32_e32 v186, v102, v204
	v_mul_f32_e32 v188, v110, v208
	v_mov_b32_e32 v189, v174
	v_mov_b32_e32 v187, v175
	v_pk_fma_f32 v[136:137], v[108:109], v[202:203], v[136:137] neg_lo:[0,0,1] neg_hi:[0,0,1]
	v_pk_fma_f32 v[138:139], v[108:109], v[206:207], v[138:139]
	v_pk_add_f32 v[174:175], v[188:189], v[186:187]
	v_pk_mul_f32 v[136:137], v[166:167], v[136:137] op_sel_hi:[0,1]
	v_pk_mul_f32 v[138:139], v[166:167], v[138:139] op_sel_hi:[0,1]
	v_pk_mul_f32 v[172:173], v[166:167], v[172:173] op_sel_hi:[0,1]
	v_pk_mul_f32 v[174:175], v[166:167], v[174:175] op_sel_hi:[0,1]

; __device__ __forceinline__ unsigned cvt_pk_bf16(float lo, float hi) { unsigned r; asm volatile("v_cvt_pk_bf16_f32 %0, %1, %2" : "=v"(r) : "v"(lo), "v"(hi)); return r; }
;     __device__ __forceinline__ void operator()(const f32x4 (&acc)[2][2][4][2], const Unit& u, int wr, int wc, int fr, int fq) const {
;     ...
;                 for (int bj = 0; bj < 2; ++bj) { f32x4 v0 = acc[ai][bj][m][0], v1 = acc[ai][bj][m][1];
;                     if (rope) {
; #pragma unroll
;                         for (int i = 0; i < 4; ++i) { const float a = v0[i], b = v1[i]; v0[i] = (a * cs[i] - b * sn[i]) * sc; v1[i] = (b * cs[i] + a * sn[i]) * sc; } }
;                     u32x4 w; w.x = cvt_pk_bf16(v0[0], v0[1]); w.y = cvt_pk_bf16(v0[2], v0[3]); w.z = cvt_pk_bf16(v1[0], v1[1]); w.w = cvt_pk_bf16(v1[2], v1[3]);
;                     if (kv) {
;                         const int cseg = (u.pn & 1) * 256 + bj * HALF + wc * 32 + 8 * fq; const unsigned hd = (unsigned)cseg >> 6, dl = ((unsigned)cseg & 63u) >> 3;
;                         const unsigned pos = (unsigned)row & 4095u, key = pos & 63u; const unsigned rb = ((unsigned)row >> 12) * 2097152u + hd * 262144u + (pos >> 6) * 4096u;
;                         if (u.pn < 8) *(u32x4*)(Kb + rb + dl * 512u + key * 8u) = w;
;                         else *(u32x4*)(Vb + rb + (dl >> 2) * 2048u + (key >> 4) * 512u + (key & 15u) * 32u + (dl & 3u) * 8u) = w;
;                     } else *(u32x4*)(rowp + bj * HALF) = w; } }
.LBB0_230:
	s_and_b64 vcc, exec, s[8:9]
	s_nop 0
	v_mov_b32_e32 v136, v104
	v_mov_b32_e32 v137, v105
	v_mov_b32_e32 v172, v106
	v_mov_b32_e32 v173, v107
	v_mov_b32_e32 v138, v96
	v_mov_b32_e32 v139, v97
	v_mov_b32_e32 v174, v98
	v_mov_b32_e32 v175, v99
	s_cbranch_vccnz .LBB0_232
	s_nop 0
	v_pk_mul_f32 v[136:137], v[96:97], v[206:207]
	v_mul_f32_e32 v186, v106, v208
	v_pk_fma_f32 v[136:137], v[104:105], v[202:203], v[136:137] neg_lo:[0,0,1] neg_hi:[0,0,1]
	v_pk_mul_f32 v[202:203], v[96:97], v[202:203]
	v_mov_b32_e32 v188, v107
	v_pk_fma_f32 v[202:203], v[104:105], v[206:207], v[202:203]
	v_mul_f32_e32 v206, v98, v208
	v_mov_b32_e32 v189, v99
	v_mov_b32_e32 v208, v205
	v_pk_mul_f32 v[172:173], v[188:189], v[208:209]
	v_pk_mul_f32 v[138:139], v[166:167], v[202:203] op_sel_hi:[0,1]
	v_mul_f32_e32 v202, v106, v204
	v_mov_b32_e32 v203, v172
	v_mov_b32_e32 v207, v173
	v_mul_f32_e32 v174, v98, v204
	v_pk_add_f32 v[202:203], v[202:203], v[206:207] neg_lo:[0,1] neg_hi:[0,1]
	v_mov_b32_e32 v204, v209
	v_pk_mul_f32 v[172:173], v[166:167], v[202:203] op_sel_hi:[0,1]
	v_pk_mul_f32 v[202:203], v[188:189], v[204:205]
	v_pk_mul_f32 v[136:137], v[166:167], v[136:137] op_sel_hi:[0,1]
	v_mov_b32_e32 v187, v202
	v_mov_b32_e32 v175, v203
	v_pk_add_f32 v[202:203], v[186:187], v[174:175]
	s_nop 0
	v_pk_mul_f32 v[174:175], v[166:167], v[202:203] op_sel_hi:[0,1]
.LBB0_232:
	s_and_b64 vcc, exec, s[6:7]
	s_mov_b64 s[48:49], -1
	s_nop 0
	v_cvt_pk_bf16_f32 v128, v136, v137
	v_cvt_pk_bf16_f32 v129, v172, v173
	v_cvt_pk_bf16_f32 v130, v138, v139
	v_cvt_pk_bf16_f32 v131, v174, v175
	s_cbranch_vccnz .LBB0_234
	s_mov_b64 s[48:49], 0
	global_store_dwordx4 v[170:171], v[128:131], off offset:256
.LBB0_234:
	s_andn2_b64 vcc, exec, s[48:49]
	s_cbranch_vccnz .LBB0_239
	s_and_b32 s48, s39, 0x100
	s_nop 0
	v_add_lshl_u32 v132, s48, v179, 12
	v_and_b32_e32 v132, 0xfffc0000, v132
	v_add_u32_e32 v148, s41, v132
	s_and_b64 vcc, exec, s[4:5]
	s_mov_b64 s[48:49], -1
	s_cbranch_vccnz .LBB0_237
	v_lshl_add_u64 v[132:133], v[148:149], 1, v[152:153]
	s_mov_b64 s[48:49], 0
	global_store_dwordx4 v[132:133], v[128:131], off offset:1024

; __device__ __forceinline__ unsigned cvt_pk_bf16(float lo, float hi) { unsigned r; asm volatile("v_cvt_pk_bf16_f32 %0, %1, %2" : "=v"(r) : "v"(lo), "v"(hi)); return r; }
;     __device__ __forceinline__ void operator()(const f32x4 (&acc)[2][2][4][2], const Unit& u, int wr, int wc, int fr, int fq) const {
;     ...
;             for (int m = 0; m < 4; ++m) { const int row = row0 + ai * HALF + m * 16; bf16_t* rowp = O + (size_t)row * ldc + col0;
;                 f32x4 cs = (f32x4){1.f, 1.f, 1.f, 1.f}, sn = (f32x4){0.f, 0.f, 0.f, 0.f};
;                 if (rope) { const float* tp = tab + (size_t)(row & 4095) * 32 + fo; cs = *(const f32x4*)tp; sn = *(const f32x4*)(tp + 4096 * 32); }
; #pragma unroll
;                 for (int bj = 0; bj < 2; ++bj) { f32x4 v0 = acc[ai][bj][m][0], v1 = acc[ai][bj][m][1];
;                     if (rope) {
; #pragma unroll
;                         for (int i = 0; i < 4; ++i) { const float a = v0[i], b = v1[i]; v0[i] = (a * cs[i] - b * sn[i]) * sc; v1[i] = (b * cs[i] + a * sn[i]) * sc; } }
;                     u32x4 w; w.x = cvt_pk_bf16(v0[0], v0[1]); w.y = cvt_pk_bf16(v0[2], v0[3]); w.z = cvt_pk_bf16(v1[0], v1[1]); w.w = cvt_pk_bf16(v1[2], v1[3]);
.LBB0_239:
	s_and_b64 vcc, exec, s[8:9]
	v_or_b32_e32 v170, 32, v184
	s_cbranch_vccnz .LBB0_241
	v_add_u32_e32 v128, 0xb0, v184
	v_lshlrev_b32_e32 v128, 7, v128
	v_and_b32_e32 v148, 0x7ff80, v128
	v_lshl_add_u64 v[128:129], v[150:151], 0, v[148:149]
	v_add_co_u32_e32 v132, vcc, 0x80000, v128
	s_nop 1
	v_addc_co_u32_e32 v133, vcc, 0, v129, vcc
	global_load_dwordx4 v[96:99], v[128:129], off
	s_nop 0
	global_load_dwordx4 v[100:103], v[132:133], off
	s_branch .LBB0_242
.LBB0_241:
	v_mov_b32_e32 v128, 1.0
	s_nop 0
	v_mov_b32_e32 v132, 0
	v_mov_b32_e32 v133, v132
	v_mov_b32_e32 v134, v132
	v_mov_b32_e32 v135, v132
	v_mov_b32_e32 v129, v128
	v_mov_b32_e32 v130, v128
	v_mov_b32_e32 v131, v128
.LBB0_242:
	s_and_b64 vcc, exec, s[8:9]
	v_mov_b32_e32 v136, v92
	v_mov_b32_e32 v137, v93
	v_mov_b32_e32 v172, v94
	v_mov_b32_e32 v173, v95
	v_mov_b32_e32 v138, v84
	v_mov_b32_e32 v139, v85
	v_mov_b32_e32 v174, v86
	v_mov_b32_e32 v175, v87
	s_cbranch_vccnz .LBB0_244
	v_mov_b32_e32 v190, v95
	v_mov_b32_e32 v191, v87
	s_waitcnt vmcnt(14)
	v_mov_b32_e32 v192, v213
	s_nop 0
	v_mov_b32_e32 v193, v217
	v_pk_mul_f32 v[192:193], v[190:191], v[192:193]
	v_mul_f32_e32 v172, v94, v212
	v_mul_f32_e32 v174, v86, v216
	v_mov_b32_e32 v173, v192
	v_mov_b32_e32 v175, v193
	v_pk_add_f32 v[172:173], v[172:173], v[174:175] neg_lo:[0,1] neg_hi:[0,1]
	v_mov_b32_e32 v174, v217
	v_mov_b32_e32 v175, v213
	v_pk_mul_f32 v[174:175], v[190:191], v[174:175]
	v_pk_mul_f32 v[136:137], v[84:85], v[214:215]
	v_pk_mul_f32 v[138:139], v[84:85], v[210:211]
	v_mul_f32_e32 v186, v86, v212
	v_mul_f32_e32 v188, v94, v216
	v_mov_b32_e32 v189, v174
	v_mov_b32_e32 v187, v175
	v_pk_fma_f32 v[136:137], v[92:93], v[210:211], v[136:137] neg_lo:[0,0,1] neg_hi:[0,0,1]
	v_pk_fma_f32 v[138:139], v[92:93], v[214:215], v[138:139]
	v_pk_add_f32 v[174:175], v[188:189], v[186:187]
	v_pk_mul_f32 v[136:137], v[166:167], v[136:137] op_sel_hi:[0,1]
	v_pk_mul_f32 v[138:139], v[166:167], v[138:139] op_sel_hi:[0,1]
	v_pk_mul_f32 v[172:173], v[166:167], v[172:173] op_sel_hi:[0,1]
	v_pk_mul_f32 v[174:175], v[166:167], v[174:175] op_sel_hi:[0,1]

; __device__ __forceinline__ unsigned cvt_pk_bf16(float lo, float hi) { unsigned r; asm volatile("v_cvt_pk_bf16_f32 %0, %1, %2" : "=v"(r) : "v"(lo), "v"(hi)); return r; }
;     __device__ __forceinline__ void operator()(const f32x4 (&acc)[2][2][4][2], const Unit& u, int wr, int wc, int fr, int fq) const {
;     ...
;                 for (int bj = 0; bj < 2; ++bj) { f32x4 v0 = acc[ai][bj][m][0], v1 = acc[ai][bj][m][1];
;                     if (rope) {
; #pragma unroll
;                         for (int i = 0; i < 4; ++i) { const float a = v0[i], b = v1[i]; v0[i] = (a * cs[i] - b * sn[i]) * sc; v1[i] = (b * cs[i] + a * sn[i]) * sc; } }
;                     u32x4 w; w.x = cvt_pk_bf16(v0[0], v0[1]); w.y = cvt_pk_bf16(v0[2], v0[3]); w.z = cvt_pk_bf16(v1[0], v1[1]); w.w = cvt_pk_bf16(v1[2], v1[3]);
.LBB0_251:
	s_and_b64 vcc, exec, s[8:9]
	s_nop 0
	v_mov_b32_e32 v136, v88
	v_mov_b32_e32 v137, v89
	v_mov_b32_e32 v172, v90
	v_mov_b32_e32 v173, v91
	v_mov_b32_e32 v138, v80
	v_mov_b32_e32 v139, v81
	v_mov_b32_e32 v174, v82
	v_mov_b32_e32 v175, v83
	s_cbranch_vccnz .LBB0_253
	s_nop 0
	v_pk_mul_f32 v[136:137], v[80:81], v[214:215]
	v_mul_f32_e32 v186, v90, v216
	v_pk_fma_f32 v[136:137], v[88:89], v[210:211], v[136:137] neg_lo:[0,0,1] neg_hi:[0,0,1]
	v_pk_mul_f32 v[210:211], v[80:81], v[210:211]
	v_mov_b32_e32 v188, v91
	v_pk_fma_f32 v[210:211], v[88:89], v[214:215], v[210:211]
	v_mul_f32_e32 v214, v82, v216
	v_mov_b32_e32 v189, v83
	v_mov_b32_e32 v216, v213
	v_pk_mul_f32 v[172:173], v[188:189], v[216:217]
	v_pk_mul_f32 v[138:139], v[166:167], v[210:211] op_sel_hi:[0,1]
	v_mul_f32_e32 v210, v90, v212
	v_mov_b32_e32 v211, v172
	v_mov_b32_e32 v215, v173
	v_mul_f32_e32 v174, v82, v212
	v_pk_add_f32 v[210:211], v[210:211], v[214:215] neg_lo:[0,1] neg_hi:[0,1]
	v_mov_b32_e32 v212, v217
	v_pk_mul_f32 v[172:173], v[166:167], v[210:211] op_sel_hi:[0,1]
	v_pk_mul_f32 v[210:211], v[188:189], v[212:213]
	v_pk_mul_f32 v[136:137], v[166:167], v[136:137] op_sel_hi:[0,1]
	v_mov_b32_e32 v187, v210
	v_mov_b32_e32 v175, v211
	v_pk_add_f32 v[210:211], v[186:187], v[174:175]
	s_nop 0
	v_pk_mul_f32 v[174:175], v[166:167], v[210:211] op_sel_hi:[0,1]

;     __device__ __forceinline__ void operator()(const f32x4 (&acc)[2][2][4][2], const Unit& u, int wr, int wc, int fr, int fq) const {
;     ...
;                     if (kv) {
;                         const int cseg = (u.pn & 1) * 256 + bj * HALF + wc * 32 + 8 * fq; const unsigned hd = (unsigned)cseg >> 6, dl = ((unsigned)cseg & 63u) >> 3;
;                         const unsigned pos = (unsigned)row & 4095u, key = pos & 63u; const unsigned rb = ((unsigned)row >> 12) * 2097152u + hd * 262144u + (pos >> 6) * 4096u;
;                         if (u.pn < 8) *(u32x4*)(Kb + rb + dl * 512u + key * 8u) = w;
;                         else *(u32x4*)(Vb + rb + (dl >> 2) * 2048u + (key >> 4) * 512u + (key & 15u) * 32u + (dl & 3u) * 8u) = w;
;                     } else *(u32x4*)(rowp + bj * HALF) = w; } }
.LBB0_255:
	s_andn2_b64 vcc, exec, s[48:49]
	s_cbranch_vccnz .LBB0_260
	s_and_b32 s48, s39, 0x100
	s_nop 0
	v_add_lshl_u32 v132, s48, v179, 12
	v_and_b32_e32 v132, 0xfffc0000, v132
	v_add_u32_e32 v148, s41, v132
	s_and_b64 vcc, exec, s[4:5]
	s_mov_b64 s[48:49], -1
	s_cbranch_vccnz .LBB0_258
	v_lshl_add_u64 v[132:133], v[148:149], 1, v[152:153]
	s_mov_b64 s[48:49], 0
	global_store_dwordx4 v[132:133], v[128:131], off offset:2048

;     __device__ __forceinline__ void operator()(const f32x4 (&acc)[2][2][4][2], const Unit& u, int wr, int wc, int fr, int fq) const {
;     ...
;             for (int m = 0; m < 4; ++m) { const int row = row0 + ai * HALF + m * 16; bf16_t* rowp = O + (size_t)row * ldc + col0;
;                 f32x4 cs = (f32x4){1.f, 1.f, 1.f, 1.f}, sn = (f32x4){0.f, 0.f, 0.f, 0.f};
;                 if (rope) { const float* tp = tab + (size_t)(row & 4095) * 32 + fo; cs = *(const f32x4*)tp; sn = *(const f32x4*)(tp + 4096 * 32); }
.LBB0_260:
	s_and_b64 vcc, exec, s[8:9]
	v_or_b32_e32 v170, 48, v184
	s_cbranch_vccnz .LBB0_262
	s_nop 0
	s_branch .LBB0_263

; __device__ __forceinline__ unsigned cvt_pk_bf16(float lo, float hi) { unsigned r; asm volatile("v_cvt_pk_bf16_f32 %0, %1, %2" : "=v"(r) : "v"(lo), "v"(hi)); return r; }
;     __device__ __forceinline__ void operator()(const f32x4 (&acc)[2][2][4][2], const Unit& u, int wr, int wc, int fr, int fq) const {
;     ...
;                 for (int bj = 0; bj < 2; ++bj) { f32x4 v0 = acc[ai][bj][m][0], v1 = acc[ai][bj][m][1];
;                     if (rope) {
; #pragma unroll
;                         for (int i = 0; i < 4; ++i) { const float a = v0[i], b = v1[i]; v0[i] = (a * cs[i] - b * sn[i]) * sc; v1[i] = (b * cs[i] + a * sn[i]) * sc; } }
;                     u32x4 w; w.x = cvt_pk_bf16(v0[0], v0[1]); w.y = cvt_pk_bf16(v0[2], v0[3]); w.z = cvt_pk_bf16(v1[0], v1[1]); w.w = cvt_pk_bf16(v1[2], v1[3]);
.LBB0_263:
	s_and_b64 vcc, exec, s[8:9]
	v_mov_b32_e32 v136, v76
	v_mov_b32_e32 v137, v77
	v_mov_b32_e32 v172, v78
	v_mov_b32_e32 v173, v79
	v_mov_b32_e32 v138, v68
	v_mov_b32_e32 v139, v69
	v_mov_b32_e32 v174, v70
	v_mov_b32_e32 v175, v71
	s_cbranch_vccnz .LBB0_265
	v_mov_b32_e32 v190, v79
	v_mov_b32_e32 v191, v71
	s_waitcnt vmcnt(14)
	v_mov_b32_e32 v192, v225
	s_nop 0
	v_mov_b32_e32 v193, v229
	v_pk_mul_f32 v[192:193], v[190:191], v[192:193]
	v_mul_f32_e32 v172, v78, v224
	v_mul_f32_e32 v174, v70, v228
	v_mov_b32_e32 v173, v192
	v_mov_b32_e32 v175, v193
	v_pk_add_f32 v[172:173], v[172:173], v[174:175] neg_lo:[0,1] neg_hi:[0,1]
	v_mov_b32_e32 v174, v229
	v_mov_b32_e32 v175, v225
	v_pk_mul_f32 v[174:175], v[190:191], v[174:175]
	v_pk_mul_f32 v[136:137], v[68:69], v[226:227]
	v_pk_mul_f32 v[138:139], v[68:69], v[222:223]
	v_mul_f32_e32 v186, v70, v224
	v_mul_f32_e32 v188, v78, v228
	v_mov_b32_e32 v189, v174
	v_mov_b32_e32 v187, v175
	v_pk_fma_f32 v[136:137], v[76:77], v[222:223], v[136:137] neg_lo:[0,0,1] neg_hi:[0,0,1]
	v_pk_fma_f32 v[138:139], v[76:77], v[226:227], v[138:139]
	v_pk_add_f32 v[174:175], v[188:189], v[186:187]
	v_pk_mul_f32 v[136:137], v[166:167], v[136:137] op_sel_hi:[0,1]
	v_pk_mul_f32 v[138:139], v[166:167], v[138:139] op_sel_hi:[0,1]
	v_pk_mul_f32 v[172:173], v[166:167], v[172:173] op_sel_hi:[0,1]
	v_pk_mul_f32 v[174:175], v[166:167], v[174:175] op_sel_hi:[0,1]

; __device__ __forceinline__ unsigned cvt_pk_bf16(float lo, float hi) { unsigned r; asm volatile("v_cvt_pk_bf16_f32 %0, %1, %2" : "=v"(r) : "v"(lo), "v"(hi)); return r; }
;     __device__ __forceinline__ void operator()(const f32x4 (&acc)[2][2][4][2], const Unit& u, int wr, int wc, int fr, int fq) const {
;     ...
;                 for (int bj = 0; bj < 2; ++bj) { f32x4 v0 = acc[ai][bj][m][0], v1 = acc[ai][bj][m][1];
;                     if (rope) {
; #pragma unroll
;                         for (int i = 0; i < 4; ++i) { const float a = v0[i], b = v1[i]; v0[i] = (a * cs[i] - b * sn[i]) * sc; v1[i] = (b * cs[i] + a * sn[i]) * sc; } }
;                     u32x4 w; w.x = cvt_pk_bf16(v0[0], v0[1]); w.y = cvt_pk_bf16(v0[2], v0[3]); w.z = cvt_pk_bf16(v1[0], v1[1]); w.w = cvt_pk_bf16(v1[2], v1[3]);
.LBB0_272:
	s_and_b64 vcc, exec, s[8:9]
	s_nop 0
	v_mov_b32_e32 v136, v72
	v_mov_b32_e32 v137, v73
	v_mov_b32_e32 v172, v74
	v_mov_b32_e32 v173, v75
	v_mov_b32_e32 v138, v64
	v_mov_b32_e32 v139, v65
	v_mov_b32_e32 v174, v66
	v_mov_b32_e32 v175, v67
	s_cbranch_vccnz .LBB0_274
	s_nop 0
	v_pk_mul_f32 v[136:137], v[64:65], v[226:227]
	v_mul_f32_e32 v186, v74, v228
	v_pk_fma_f32 v[136:137], v[72:73], v[222:223], v[136:137] neg_lo:[0,0,1] neg_hi:[0,0,1]
	v_pk_mul_f32 v[222:223], v[64:65], v[222:223]
	v_mov_b32_e32 v188, v75
	v_pk_fma_f32 v[222:223], v[72:73], v[226:227], v[222:223]
	v_mul_f32_e32 v226, v66, v228
	v_mov_b32_e32 v189, v67
	v_mov_b32_e32 v228, v225
	v_pk_mul_f32 v[172:173], v[188:189], v[228:229]
	v_pk_mul_f32 v[138:139], v[166:167], v[222:223] op_sel_hi:[0,1]
	v_mul_f32_e32 v222, v74, v224
	v_mov_b32_e32 v223, v172
	v_mov_b32_e32 v227, v173
	v_mul_f32_e32 v174, v66, v224
	v_pk_add_f32 v[222:223], v[222:223], v[226:227] neg_lo:[0,1] neg_hi:[0,1]
	v_mov_b32_e32 v224, v229
	v_pk_mul_f32 v[172:173], v[166:167], v[222:223] op_sel_hi:[0,1]
	v_pk_mul_f32 v[222:223], v[188:189], v[224:225]
	v_pk_mul_f32 v[136:137], v[166:167], v[136:137] op_sel_hi:[0,1]
	v_mov_b32_e32 v187, v222
	v_mov_b32_e32 v175, v223
	v_pk_add_f32 v[222:223], v[186:187], v[174:175]
	s_nop 0
	v_pk_mul_f32 v[174:175], v[166:167], v[222:223] op_sel_hi:[0,1]

;     __device__ __forceinline__ void operator()(const f32x4 (&acc)[2][2][4][2], const Unit& u, int wr, int wc, int fr, int fq) const {
;     ...
;                     if (kv) {
;                         const int cseg = (u.pn & 1) * 256 + bj * HALF + wc * 32 + 8 * fq; const unsigned hd = (unsigned)cseg >> 6, dl = ((unsigned)cseg & 63u) >> 3;
;                         const unsigned pos = (unsigned)row & 4095u, key = pos & 63u; const unsigned rb = ((unsigned)row >> 12) * 2097152u + hd * 262144u + (pos >> 6) * 4096u;
;                         if (u.pn < 8) *(u32x4*)(Kb + rb + dl * 512u + key * 8u) = w;
;                         else *(u32x4*)(Vb + rb + (dl >> 2) * 2048u + (key >> 4) * 512u + (key & 15u) * 32u + (dl & 3u) * 8u) = w;
;                     } else *(u32x4*)(rowp + bj * HALF) = w; } }
.LBB0_276:
	s_andn2_b64 vcc, exec, s[48:49]
	s_cbranch_vccnz .LBB0_281
	s_and_b32 s48, s39, 0x100
	s_nop 0
	v_add_lshl_u32 v132, s48, v179, 12
	v_and_b32_e32 v132, 0xfffc0000, v132
	v_add_u32_e32 v148, s41, v132
	s_and_b64 vcc, exec, s[4:5]
	s_mov_b64 s[48:49], -1
	s_cbranch_vccnz .LBB0_279
	v_lshl_add_u64 v[132:133], v[148:149], 1, v[152:153]
	s_mov_b64 s[48:49], 0
	global_store_dwordx4 v[132:133], v[128:131], off offset:3072

;     __device__ __forceinline__ void operator()(const f32x4 (&acc)[2][2][4][2], const Unit& u, int wr, int wc, int fr, int fq) const {
;     ...
;             for (int m = 0; m < 4; ++m) { const int row = row0 + ai * HALF + m * 16; bf16_t* rowp = O + (size_t)row * ldc + col0;
;                 f32x4 cs = (f32x4){1.f, 1.f, 1.f, 1.f}, sn = (f32x4){0.f, 0.f, 0.f, 0.f};
;                 if (rope) { const float* tp = tab + (size_t)(row & 4095) * 32 + fo; cs = *(const f32x4*)tp; sn = *(const f32x4*)(tp + 4096 * 32); }
.LBB0_281:
	s_and_b64 vcc, exec, s[8:9]
	v_add_u32_e32 v185, 0x80, v184
	s_cbranch_vccnz .LBB0_283
	s_nop 0
	s_branch .LBB0_284

; __device__ __forceinline__ unsigned cvt_pk_bf16(float lo, float hi) { unsigned r; asm volatile("v_cvt_pk_bf16_f32 %0, %1, %2" : "=v"(r) : "v"(lo), "v"(hi)); return r; }
;     __device__ __forceinline__ void operator()(const f32x4 (&acc)[2][2][4][2], const Unit& u, int wr, int wc, int fr, int fq) const {
;     ...
;                 for (int bj = 0; bj < 2; ++bj) { f32x4 v0 = acc[ai][bj][m][0], v1 = acc[ai][bj][m][1];
;                     if (rope) {
; #pragma unroll
;                         for (int i = 0; i < 4; ++i) { const float a = v0[i], b = v1[i]; v0[i] = (a * cs[i] - b * sn[i]) * sc; v1[i] = (b * cs[i] + a * sn[i]) * sc; } }
;                     u32x4 w; w.x = cvt_pk_bf16(v0[0], v0[1]); w.y = cvt_pk_bf16(v0[2], v0[3]); w.z = cvt_pk_bf16(v1[0], v1[1]); w.w = cvt_pk_bf16(v1[2], v1[3]);
.LBB0_284:
	s_and_b64 vcc, exec, s[8:9]
	v_mov_b32_e32 v136, v60
	v_mov_b32_e32 v137, v61
	v_mov_b32_e32 v172, v62
	v_mov_b32_e32 v173, v63
	v_mov_b32_e32 v138, v52
	v_mov_b32_e32 v139, v53
	v_mov_b32_e32 v174, v54
	v_mov_b32_e32 v175, v55
	s_cbranch_vccnz .LBB0_286
	v_mov_b32_e32 v188, v63
	v_mov_b32_e32 v189, v55
	s_waitcnt vmcnt(14)
	v_mov_b32_e32 v190, v233
	s_nop 0
	v_mov_b32_e32 v191, v237
	v_pk_mul_f32 v[190:191], v[188:189], v[190:191]
	v_mul_f32_e32 v170, v62, v232
	v_mul_f32_e32 v172, v54, v236
	v_mov_b32_e32 v171, v190
	v_mov_b32_e32 v173, v191
	v_pk_add_f32 v[170:171], v[170:171], v[172:173] neg_lo:[0,1] neg_hi:[0,1]
	v_pk_mul_f32 v[136:137], v[52:53], v[234:235]
	v_pk_mul_f32 v[172:173], v[166:167], v[170:171] op_sel_hi:[0,1]
	v_mov_b32_e32 v170, v237
	v_mov_b32_e32 v171, v233
	v_pk_mul_f32 v[170:171], v[188:189], v[170:171]
	v_pk_mul_f32 v[138:139], v[52:53], v[230:231]
	v_mul_f32_e32 v174, v54, v232
	v_mul_f32_e32 v186, v62, v236
	v_mov_b32_e32 v187, v170
	v_mov_b32_e32 v175, v171
	v_pk_fma_f32 v[136:137], v[60:61], v[230:231], v[136:137] neg_lo:[0,0,1] neg_hi:[0,0,1]
	v_pk_fma_f32 v[138:139], v[60:61], v[234:235], v[138:139]
	v_pk_add_f32 v[170:171], v[186:187], v[174:175]
	v_pk_mul_f32 v[136:137], v[166:167], v[136:137] op_sel_hi:[0,1]
	v_pk_mul_f32 v[138:139], v[166:167], v[138:139] op_sel_hi:[0,1]
	v_pk_mul_f32 v[174:175], v[166:167], v[170:171] op_sel_hi:[0,1]

; __device__ __forceinline__ unsigned cvt_pk_bf16(float lo, float hi) { unsigned r; asm volatile("v_cvt_pk_bf16_f32 %0, %1, %2" : "=v"(r) : "v"(lo), "v"(hi)); return r; }
;     __device__ __forceinline__ void operator()(const f32x4 (&acc)[2][2][4][2], const Unit& u, int wr, int wc, int fr, int fq) const {
;     ...
;                 for (int bj = 0; bj < 2; ++bj) { f32x4 v0 = acc[ai][bj][m][0], v1 = acc[ai][bj][m][1];
;                     if (rope) {
; #pragma unroll
;                         for (int i = 0; i < 4; ++i) { const float a = v0[i], b = v1[i]; v0[i] = (a * cs[i] - b * sn[i]) * sc; v1[i] = (b * cs[i] + a * sn[i]) * sc; } }
;                     u32x4 w; w.x = cvt_pk_bf16(v0[0], v0[1]); w.y = cvt_pk_bf16(v0[2], v0[3]); w.z = cvt_pk_bf16(v1[0], v1[1]); w.w = cvt_pk_bf16(v1[2], v1[3]);
.LBB0_293:
	s_and_b64 vcc, exec, s[8:9]
	s_nop 0
	v_mov_b32_e32 v136, v56
	v_mov_b32_e32 v137, v57
	v_mov_b32_e32 v172, v58
	v_mov_b32_e32 v173, v59
	v_mov_b32_e32 v138, v48
	v_mov_b32_e32 v139, v49
	v_mov_b32_e32 v174, v50
	v_mov_b32_e32 v175, v51
	s_cbranch_vccnz .LBB0_295
	s_nop 0
	v_pk_mul_f32 v[136:137], v[48:49], v[234:235]
	v_mul_f32_e32 v186, v58, v236
	v_pk_fma_f32 v[136:137], v[56:57], v[230:231], v[136:137] neg_lo:[0,0,1] neg_hi:[0,0,1]
	v_pk_mul_f32 v[230:231], v[48:49], v[230:231]
	v_mov_b32_e32 v188, v59
	v_pk_fma_f32 v[230:231], v[56:57], v[234:235], v[230:231]
	v_mul_f32_e32 v234, v50, v236
	v_mov_b32_e32 v189, v51
	v_mov_b32_e32 v236, v233
	v_pk_mul_f32 v[172:173], v[188:189], v[236:237]
	v_pk_mul_f32 v[138:139], v[166:167], v[230:231] op_sel_hi:[0,1]
	v_mul_f32_e32 v230, v58, v232
	v_mov_b32_e32 v231, v172
	v_mov_b32_e32 v235, v173
	v_mul_f32_e32 v174, v50, v232
	v_pk_add_f32 v[230:231], v[230:231], v[234:235] neg_lo:[0,1] neg_hi:[0,1]
	v_mov_b32_e32 v232, v237
	v_pk_mul_f32 v[172:173], v[166:167], v[230:231] op_sel_hi:[0,1]
	v_pk_mul_f32 v[230:231], v[188:189], v[232:233]
	v_pk_mul_f32 v[136:137], v[166:167], v[136:137] op_sel_hi:[0,1]
	v_mov_b32_e32 v187, v230
	v_mov_b32_e32 v175, v231
	v_pk_add_f32 v[230:231], v[186:187], v[174:175]
	s_nop 0
	v_pk_mul_f32 v[174:175], v[166:167], v[230:231] op_sel_hi:[0,1]

;     __device__ __forceinline__ void operator()(const f32x4 (&acc)[2][2][4][2], const Unit& u, int wr, int wc, int fr, int fq) const {
;     ...
;                     if (kv) {
;                         const int cseg = (u.pn & 1) * 256 + bj * HALF + wc * 32 + 8 * fq; const unsigned hd = (unsigned)cseg >> 6, dl = ((unsigned)cseg & 63u) >> 3;
;                         const unsigned pos = (unsigned)row & 4095u, key = pos & 63u; const unsigned rb = ((unsigned)row >> 12) * 2097152u + hd * 262144u + (pos >> 6) * 4096u;
;                         if (u.pn < 8) *(u32x4*)(Kb + rb + dl * 512u + key * 8u) = w;
;                         else *(u32x4*)(Vb + rb + (dl >> 2) * 2048u + (key >> 4) * 512u + (key & 15u) * 32u + (dl & 3u) * 8u) = w;
;                     } else *(u32x4*)(rowp + bj * HALF) = w; } }
.LBB0_297:
	s_andn2_b64 vcc, exec, s[48:49]
	s_cbranch_vccnz .LBB0_302
	s_and_b32 s41, s39, 0x100
	s_nop 0
	v_add_lshl_u32 v132, s41, v179, 12
	v_and_b32_e32 v132, 0xfffc0000, v132
	v_add_u32_e32 v148, v185, v132
	s_and_b64 vcc, exec, s[4:5]
	s_mov_b64 s[48:49], -1
	s_cbranch_vccnz .LBB0_300
	v_lshl_add_u64 v[132:133], v[148:149], 1, v[152:153]
	s_mov_b64 s[48:49], 0
	global_store_dwordx4 v[132:133], v[128:131], off

;     __device__ __forceinline__ void operator()(const f32x4 (&acc)[2][2][4][2], const Unit& u, int wr, int wc, int fr, int fq) const {
;     ...
;             for (int m = 0; m < 4; ++m) { const int row = row0 + ai * HALF + m * 16; bf16_t* rowp = O + (size_t)row * ldc + col0;
;                 f32x4 cs = (f32x4){1.f, 1.f, 1.f, 1.f}, sn = (f32x4){0.f, 0.f, 0.f, 0.f};
;                 if (rope) { const float* tp = tab + (size_t)(row & 4095) * 32 + fo; cs = *(const f32x4*)tp; sn = *(const f32x4*)(tp + 4096 * 32); }
.LBB0_302:
	s_and_b64 vcc, exec, s[8:9]
	v_add_u32_e32 v170, 0x90, v184
	s_cbranch_vccnz .LBB0_304
	s_nop 0
	s_branch .LBB0_305

; __device__ __forceinline__ unsigned cvt_pk_bf16(float lo, float hi) { unsigned r; asm volatile("v_cvt_pk_bf16_f32 %0, %1, %2" : "=v"(r) : "v"(lo), "v"(hi)); return r; }
;     __device__ __forceinline__ void operator()(const f32x4 (&acc)[2][2][4][2], const Unit& u, int wr, int wc, int fr, int fq) const {
;     ...
;                 for (int bj = 0; bj < 2; ++bj) { f32x4 v0 = acc[ai][bj][m][0], v1 = acc[ai][bj][m][1];
;                     if (rope) {
; #pragma unroll
;                         for (int i = 0; i < 4; ++i) { const float a = v0[i], b = v1[i]; v0[i] = (a * cs[i] - b * sn[i]) * sc; v1[i] = (b * cs[i] + a * sn[i]) * sc; } }
;                     u32x4 w; w.x = cvt_pk_bf16(v0[0], v0[1]); w.y = cvt_pk_bf16(v0[2], v0[3]); w.z = cvt_pk_bf16(v1[0], v1[1]); w.w = cvt_pk_bf16(v1[2], v1[3]);
.LBB0_305:
	s_and_b64 vcc, exec, s[8:9]
	v_mov_b32_e32 v136, v44
	v_mov_b32_e32 v137, v45
	v_mov_b32_e32 v172, v46
	v_mov_b32_e32 v173, v47
	v_mov_b32_e32 v138, v36
	v_mov_b32_e32 v139, v37
	v_mov_b32_e32 v174, v38
	v_mov_b32_e32 v175, v39
	s_cbranch_vccnz .LBB0_307
	v_mov_b32_e32 v190, v47
	v_mov_b32_e32 v191, v39
	s_waitcnt vmcnt(12)
	v_mov_b32_e32 v192, v115
	s_nop 0
	v_mov_b32_e32 v193, v119
	v_pk_mul_f32 v[192:193], v[190:191], v[192:193]
	v_mul_f32_e32 v172, v46, v114
	v_mul_f32_e32 v174, v38, v118
	v_mov_b32_e32 v173, v192
	v_mov_b32_e32 v175, v193
	v_pk_add_f32 v[172:173], v[172:173], v[174:175] neg_lo:[0,1] neg_hi:[0,1]
	v_mov_b32_e32 v174, v119
	v_mov_b32_e32 v175, v115
	v_pk_mul_f32 v[174:175], v[190:191], v[174:175]
	v_pk_mul_f32 v[136:137], v[36:37], v[116:117]
	v_pk_mul_f32 v[138:139], v[36:37], v[112:113]
	v_mul_f32_e32 v186, v38, v114
	v_mul_f32_e32 v188, v46, v118
	v_mov_b32_e32 v189, v174
	v_mov_b32_e32 v187, v175
	v_pk_fma_f32 v[136:137], v[44:45], v[112:113], v[136:137] neg_lo:[0,0,1] neg_hi:[0,0,1]
	v_pk_fma_f32 v[138:139], v[44:45], v[116:117], v[138:139]
	v_pk_add_f32 v[174:175], v[188:189], v[186:187]
	v_pk_mul_f32 v[136:137], v[166:167], v[136:137] op_sel_hi:[0,1]
	v_pk_mul_f32 v[138:139], v[166:167], v[138:139] op_sel_hi:[0,1]
	v_pk_mul_f32 v[172:173], v[166:167], v[172:173] op_sel_hi:[0,1]
	v_pk_mul_f32 v[174:175], v[166:167], v[174:175] op_sel_hi:[0,1]

; __device__ __forceinline__ unsigned cvt_pk_bf16(float lo, float hi) { unsigned r; asm volatile("v_cvt_pk_bf16_f32 %0, %1, %2" : "=v"(r) : "v"(lo), "v"(hi)); return r; }
;     __device__ __forceinline__ void operator()(const f32x4 (&acc)[2][2][4][2], const Unit& u, int wr, int wc, int fr, int fq) const {
;     ...
;                 for (int bj = 0; bj < 2; ++bj) { f32x4 v0 = acc[ai][bj][m][0], v1 = acc[ai][bj][m][1];
;                     if (rope) {
; #pragma unroll
;                         for (int i = 0; i < 4; ++i) { const float a = v0[i], b = v1[i]; v0[i] = (a * cs[i] - b * sn[i]) * sc; v1[i] = (b * cs[i] + a * sn[i]) * sc; } }
;                     u32x4 w; w.x = cvt_pk_bf16(v0[0], v0[1]); w.y = cvt_pk_bf16(v0[2], v0[3]); w.z = cvt_pk_bf16(v1[0], v1[1]); w.w = cvt_pk_bf16(v1[2], v1[3]);
.LBB0_314:
	s_and_b64 vcc, exec, s[8:9]
	s_nop 0
	v_mov_b32_e32 v136, v40
	v_mov_b32_e32 v137, v41
	v_mov_b32_e32 v172, v42
	v_mov_b32_e32 v173, v43
	v_mov_b32_e32 v138, v32
	v_mov_b32_e32 v139, v33
	v_mov_b32_e32 v174, v34
	v_mov_b32_e32 v175, v35
	s_cbranch_vccnz .LBB0_316
	s_nop 0
	v_pk_mul_f32 v[136:137], v[32:33], v[116:117]
	v_mul_f32_e32 v186, v42, v118
	v_pk_fma_f32 v[136:137], v[40:41], v[112:113], v[136:137] neg_lo:[0,0,1] neg_hi:[0,0,1]
	v_pk_mul_f32 v[112:113], v[32:33], v[112:113]
	v_mov_b32_e32 v188, v43
	v_pk_fma_f32 v[112:113], v[40:41], v[116:117], v[112:113]
	v_mul_f32_e32 v116, v34, v118
	v_mov_b32_e32 v189, v35
	v_mov_b32_e32 v118, v115
	v_pk_mul_f32 v[172:173], v[188:189], v[118:119]
	v_pk_mul_f32 v[138:139], v[166:167], v[112:113] op_sel_hi:[0,1]
	v_mul_f32_e32 v112, v42, v114
	v_mov_b32_e32 v113, v172
	v_mov_b32_e32 v117, v173
	v_mul_f32_e32 v174, v34, v114
	v_pk_add_f32 v[112:113], v[112:113], v[116:117] neg_lo:[0,1] neg_hi:[0,1]
	v_mov_b32_e32 v114, v119
	v_pk_mul_f32 v[172:173], v[166:167], v[112:113] op_sel_hi:[0,1]
	v_pk_mul_f32 v[112:113], v[188:189], v[114:115]
	v_pk_mul_f32 v[136:137], v[166:167], v[136:137] op_sel_hi:[0,1]
	v_mov_b32_e32 v187, v112
	v_mov_b32_e32 v175, v113
	v_pk_add_f32 v[112:113], v[186:187], v[174:175]
	s_nop 0
	v_pk_mul_f32 v[174:175], v[166:167], v[112:113] op_sel_hi:[0,1]

;     __device__ __forceinline__ void operator()(const f32x4 (&acc)[2][2][4][2], const Unit& u, int wr, int wc, int fr, int fq) const {
;     ...
;                     if (kv) {
;                         const int cseg = (u.pn & 1) * 256 + bj * HALF + wc * 32 + 8 * fq; const unsigned hd = (unsigned)cseg >> 6, dl = ((unsigned)cseg & 63u) >> 3;
;                         const unsigned pos = (unsigned)row & 4095u, key = pos & 63u; const unsigned rb = ((unsigned)row >> 12) * 2097152u + hd * 262144u + (pos >> 6) * 4096u;
;                         if (u.pn < 8) *(u32x4*)(Kb + rb + dl * 512u + key * 8u) = w;
;                         else *(u32x4*)(Vb + rb + (dl >> 2) * 2048u + (key >> 4) * 512u + (key & 15u) * 32u + (dl & 3u) * 8u) = w;
;                     } else *(u32x4*)(rowp + bj * HALF) = w; } }
.LBB0_318:
	s_andn2_b64 vcc, exec, s[48:49]
	s_cbranch_vccnz .LBB0_323
	s_and_b32 s41, s39, 0x100
	s_nop 0
	v_add_lshl_u32 v132, s41, v179, 12
	v_and_b32_e32 v132, 0xfffc0000, v132
	v_add_u32_e32 v148, v185, v132
	s_and_b64 vcc, exec, s[4:5]
	s_mov_b64 s[48:49], -1
	s_cbranch_vccnz .LBB0_321
	v_lshl_add_u64 v[132:133], v[148:149], 1, v[152:153]
	s_mov_b64 s[48:49], 0
	global_store_dwordx4 v[132:133], v[128:131], off offset:1024

;     __device__ __forceinline__ void operator()(const f32x4 (&acc)[2][2][4][2], const Unit& u, int wr, int wc, int fr, int fq) const {
;     ...
;             for (int m = 0; m < 4; ++m) { const int row = row0 + ai * HALF + m * 16; bf16_t* rowp = O + (size_t)row * ldc + col0;
;                 f32x4 cs = (f32x4){1.f, 1.f, 1.f, 1.f}, sn = (f32x4){0.f, 0.f, 0.f, 0.f};
;                 if (rope) { const float* tp = tab + (size_t)(row & 4095) * 32 + fo; cs = *(const f32x4*)tp; sn = *(const f32x4*)(tp + 4096 * 32); }
.LBB0_323:
	s_and_b64 vcc, exec, s[8:9]
	v_add_u32_e32 v170, 0xa0, v184
	s_cbranch_vccnz .LBB0_325
	s_nop 0
	s_branch .LBB0_326

; __device__ __forceinline__ unsigned cvt_pk_bf16(float lo, float hi) { unsigned r; asm volatile("v_cvt_pk_bf16_f32 %0, %1, %2" : "=v"(r) : "v"(lo), "v"(hi)); return r; }
;     __device__ __forceinline__ void operator()(const f32x4 (&acc)[2][2][4][2], const Unit& u, int wr, int wc, int fr, int fq) const {
;     ...
;                 for (int bj = 0; bj < 2; ++bj) { f32x4 v0 = acc[ai][bj][m][0], v1 = acc[ai][bj][m][1];
;                     if (rope) {
; #pragma unroll
;                         for (int i = 0; i < 4; ++i) { const float a = v0[i], b = v1[i]; v0[i] = (a * cs[i] - b * sn[i]) * sc; v1[i] = (b * cs[i] + a * sn[i]) * sc; } }
;                     u32x4 w; w.x = cvt_pk_bf16(v0[0], v0[1]); w.y = cvt_pk_bf16(v0[2], v0[3]); w.z = cvt_pk_bf16(v1[0], v1[1]); w.w = cvt_pk_bf16(v1[2], v1[3]);
.LBB0_326:
	s_and_b64 vcc, exec, s[8:9]
	v_mov_b32_e32 v136, v28
	v_mov_b32_e32 v137, v29
	v_mov_b32_e32 v172, v30
	v_mov_b32_e32 v173, v31
	v_mov_b32_e32 v138, v20
	v_mov_b32_e32 v139, v21
	v_mov_b32_e32 v174, v22
	v_mov_b32_e32 v175, v23
	s_cbranch_vccnz .LBB0_328
	v_mov_b32_e32 v190, v31
	v_mov_b32_e32 v191, v23
	s_waitcnt vmcnt(12)
	v_mov_b32_e32 v192, v123
	s_nop 0
	v_mov_b32_e32 v193, v127
	v_pk_mul_f32 v[192:193], v[190:191], v[192:193]
	v_mul_f32_e32 v172, v30, v122
	v_mul_f32_e32 v174, v22, v126
	v_mov_b32_e32 v173, v192
	v_mov_b32_e32 v175, v193
	v_pk_add_f32 v[172:173], v[172:173], v[174:175] neg_lo:[0,1] neg_hi:[0,1]
	v_mov_b32_e32 v174, v127
	v_mov_b32_e32 v175, v123
	v_pk_mul_f32 v[174:175], v[190:191], v[174:175]
	v_pk_mul_f32 v[136:137], v[20:21], v[124:125]
	v_pk_mul_f32 v[138:139], v[20:21], v[120:121]
	v_mul_f32_e32 v186, v22, v122
	v_mul_f32_e32 v188, v30, v126
	v_mov_b32_e32 v189, v174
	v_mov_b32_e32 v187, v175
	v_pk_fma_f32 v[136:137], v[28:29], v[120:121], v[136:137] neg_lo:[0,0,1] neg_hi:[0,0,1]
	v_pk_fma_f32 v[138:139], v[28:29], v[124:125], v[138:139]
	v_pk_add_f32 v[174:175], v[188:189], v[186:187]
	v_pk_mul_f32 v[136:137], v[166:167], v[136:137] op_sel_hi:[0,1]
	v_pk_mul_f32 v[138:139], v[166:167], v[138:139] op_sel_hi:[0,1]
	v_pk_mul_f32 v[172:173], v[166:167], v[172:173] op_sel_hi:[0,1]
	v_pk_mul_f32 v[174:175], v[166:167], v[174:175] op_sel_hi:[0,1]

; __device__ __forceinline__ unsigned cvt_pk_bf16(float lo, float hi) { unsigned r; asm volatile("v_cvt_pk_bf16_f32 %0, %1, %2" : "=v"(r) : "v"(lo), "v"(hi)); return r; }
;     __device__ __forceinline__ void operator()(const f32x4 (&acc)[2][2][4][2], const Unit& u, int wr, int wc, int fr, int fq) const {
;     ...
;                 for (int bj = 0; bj < 2; ++bj) { f32x4 v0 = acc[ai][bj][m][0], v1 = acc[ai][bj][m][1];
;                     if (rope) {
; #pragma unroll
;                         for (int i = 0; i < 4; ++i) { const float a = v0[i], b = v1[i]; v0[i] = (a * cs[i] - b * sn[i]) * sc; v1[i] = (b * cs[i] + a * sn[i]) * sc; } }
;                     u32x4 w; w.x = cvt_pk_bf16(v0[0], v0[1]); w.y = cvt_pk_bf16(v0[2], v0[3]); w.z = cvt_pk_bf16(v1[0], v1[1]); w.w = cvt_pk_bf16(v1[2], v1[3]);
.LBB0_335:
	s_and_b64 vcc, exec, s[8:9]
	s_nop 0
	v_mov_b32_e32 v136, v24
	v_mov_b32_e32 v137, v25
	v_mov_b32_e32 v172, v26
	v_mov_b32_e32 v173, v27
	v_mov_b32_e32 v138, v16
	v_mov_b32_e32 v139, v17
	v_mov_b32_e32 v174, v18
	v_mov_b32_e32 v175, v19
	s_cbranch_vccnz .LBB0_337
	s_nop 0
	v_pk_mul_f32 v[136:137], v[16:17], v[124:125]
	v_mul_f32_e32 v186, v26, v126
	v_pk_fma_f32 v[136:137], v[24:25], v[120:121], v[136:137] neg_lo:[0,0,1] neg_hi:[0,0,1]
	v_pk_mul_f32 v[120:121], v[16:17], v[120:121]
	v_mov_b32_e32 v188, v27
	v_pk_fma_f32 v[120:121], v[24:25], v[124:125], v[120:121]
	v_mul_f32_e32 v124, v18, v126
	v_mov_b32_e32 v189, v19
	v_mov_b32_e32 v126, v123
	v_pk_mul_f32 v[172:173], v[188:189], v[126:127]
	v_pk_mul_f32 v[138:139], v[166:167], v[120:121] op_sel_hi:[0,1]
	v_mul_f32_e32 v120, v26, v122
	v_mov_b32_e32 v121, v172
	v_mov_b32_e32 v125, v173
	v_mul_f32_e32 v174, v18, v122
	v_pk_add_f32 v[120:121], v[120:121], v[124:125] neg_lo:[0,1] neg_hi:[0,1]
	v_mov_b32_e32 v122, v127
	v_pk_mul_f32 v[172:173], v[166:167], v[120:121] op_sel_hi:[0,1]
	v_pk_mul_f32 v[120:121], v[188:189], v[122:123]
	v_pk_mul_f32 v[136:137], v[166:167], v[136:137] op_sel_hi:[0,1]
	v_mov_b32_e32 v187, v120
	v_mov_b32_e32 v175, v121
	v_pk_add_f32 v[120:121], v[186:187], v[174:175]
	s_nop 0
	v_pk_mul_f32 v[174:175], v[166:167], v[120:121] op_sel_hi:[0,1]

;     __device__ __forceinline__ void operator()(const f32x4 (&acc)[2][2][4][2], const Unit& u, int wr, int wc, int fr, int fq) const {
;     ...
;                     if (kv) {
;                         const int cseg = (u.pn & 1) * 256 + bj * HALF + wc * 32 + 8 * fq; const unsigned hd = (unsigned)cseg >> 6, dl = ((unsigned)cseg & 63u) >> 3;
;                         const unsigned pos = (unsigned)row & 4095u, key = pos & 63u; const unsigned rb = ((unsigned)row >> 12) * 2097152u + hd * 262144u + (pos >> 6) * 4096u;
;                         if (u.pn < 8) *(u32x4*)(Kb + rb + dl * 512u + key * 8u) = w;
;                         else *(u32x4*)(Vb + rb + (dl >> 2) * 2048u + (key >> 4) * 512u + (key & 15u) * 32u + (dl & 3u) * 8u) = w;
;                     } else *(u32x4*)(rowp + bj * HALF) = w; } }
.LBB0_339:
	s_andn2_b64 vcc, exec, s[48:49]
	s_cbranch_vccnz .LBB0_344
	s_and_b32 s41, s39, 0x100
	s_nop 0
	v_add_lshl_u32 v132, s41, v179, 12
	v_and_b32_e32 v132, 0xfffc0000, v132
	v_add_u32_e32 v148, v185, v132
	s_and_b64 vcc, exec, s[4:5]
	s_mov_b64 s[48:49], -1
	s_cbranch_vccnz .LBB0_342
	v_lshl_add_u64 v[132:133], v[148:149], 1, v[152:153]
	s_mov_b64 s[48:49], 0
	global_store_dwordx4 v[132:133], v[128:131], off offset:2048

;     __device__ __forceinline__ void operator()(const f32x4 (&acc)[2][2][4][2], const Unit& u, int wr, int wc, int fr, int fq) const {
;     ...
;             for (int m = 0; m < 4; ++m) { const int row = row0 + ai * HALF + m * 16; bf16_t* rowp = O + (size_t)row * ldc + col0;
;                 f32x4 cs = (f32x4){1.f, 1.f, 1.f, 1.f}, sn = (f32x4){0.f, 0.f, 0.f, 0.f};
;                 if (rope) { const float* tp = tab + (size_t)(row & 4095) * 32 + fo; cs = *(const f32x4*)tp; sn = *(const f32x4*)(tp + 4096 * 32); }
.LBB0_344:
	s_and_b64 vcc, exec, s[8:9]
	v_add_u32_e32 v174, 0xb0, v184
	s_cbranch_vccnz .LBB0_346
	s_nop 0
	s_branch .LBB0_347

; __device__ __forceinline__ unsigned cvt_pk_bf16(float lo, float hi) { unsigned r; asm volatile("v_cvt_pk_bf16_f32 %0, %1, %2" : "=v"(r) : "v"(lo), "v"(hi)); return r; }
;     __device__ __forceinline__ void operator()(const f32x4 (&acc)[2][2][4][2], const Unit& u, int wr, int wc, int fr, int fq) const {
;     ...
;                 for (int bj = 0; bj < 2; ++bj) { f32x4 v0 = acc[ai][bj][m][0], v1 = acc[ai][bj][m][1];
;                     if (rope) {
; #pragma unroll
;                         for (int i = 0; i < 4; ++i) { const float a = v0[i], b = v1[i]; v0[i] = (a * cs[i] - b * sn[i]) * sc; v1[i] = (b * cs[i] + a * sn[i]) * sc; } }
;                     u32x4 w; w.x = cvt_pk_bf16(v0[0], v0[1]); w.y = cvt_pk_bf16(v0[2], v0[3]); w.z = cvt_pk_bf16(v1[0], v1[1]); w.w = cvt_pk_bf16(v1[2], v1[3]);
.LBB0_347:
	s_and_b64 vcc, exec, s[8:9]
	v_mov_b32_e32 v136, v12
	v_mov_b32_e32 v137, v13
	v_mov_b32_e32 v170, v14
	v_mov_b32_e32 v171, v15
	v_mov_b32_e32 v138, v4
	v_mov_b32_e32 v139, v5
	v_mov_b32_e32 v172, v6
	v_mov_b32_e32 v173, v7
	s_cbranch_vccnz .LBB0_349
	v_mov_b32_e32 v190, v15
	v_mov_b32_e32 v191, v7
	s_waitcnt vmcnt(10)
	v_mov_b32_e32 v192, v99
	s_nop 0
	v_mov_b32_e32 v193, v103
	v_pk_mul_f32 v[192:193], v[190:191], v[192:193]
	v_mul_f32_e32 v170, v14, v98
	v_mul_f32_e32 v172, v6, v102
	v_mov_b32_e32 v171, v192
	v_mov_b32_e32 v173, v193
	v_pk_add_f32 v[170:171], v[170:171], v[172:173] neg_lo:[0,1] neg_hi:[0,1]
	v_mov_b32_e32 v172, v103
	v_mov_b32_e32 v173, v99
	v_pk_mul_f32 v[172:173], v[190:191], v[172:173]
	v_pk_mul_f32 v[136:137], v[4:5], v[100:101]
	v_pk_mul_f32 v[138:139], v[4:5], v[96:97]
	v_mul_f32_e32 v186, v6, v98
	v_mul_f32_e32 v188, v14, v102
	v_mov_b32_e32 v189, v172
	v_mov_b32_e32 v187, v173
	v_pk_fma_f32 v[136:137], v[12:13], v[96:97], v[136:137] neg_lo:[0,0,1] neg_hi:[0,0,1]
	v_pk_fma_f32 v[138:139], v[12:13], v[100:101], v[138:139]
	v_pk_add_f32 v[172:173], v[188:189], v[186:187]
	v_pk_mul_f32 v[136:137], v[166:167], v[136:137] op_sel_hi:[0,1]
	v_pk_mul_f32 v[138:139], v[166:167], v[138:139] op_sel_hi:[0,1]
	v_pk_mul_f32 v[170:171], v[166:167], v[170:171] op_sel_hi:[0,1]
	v_pk_mul_f32 v[172:173], v[166:167], v[172:173] op_sel_hi:[0,1]

; __device__ __forceinline__ unsigned cvt_pk_bf16(float lo, float hi) { unsigned r; asm volatile("v_cvt_pk_bf16_f32 %0, %1, %2" : "=v"(r) : "v"(lo), "v"(hi)); return r; }
;     __device__ __forceinline__ void operator()(const f32x4 (&acc)[2][2][4][2], const Unit& u, int wr, int wc, int fr, int fq) const {
;     ...
;                 for (int bj = 0; bj < 2; ++bj) { f32x4 v0 = acc[ai][bj][m][0], v1 = acc[ai][bj][m][1];
;                     if (rope) {
; #pragma unroll
;                         for (int i = 0; i < 4; ++i) { const float a = v0[i], b = v1[i]; v0[i] = (a * cs[i] - b * sn[i]) * sc; v1[i] = (b * cs[i] + a * sn[i]) * sc; } }
;                     u32x4 w; w.x = cvt_pk_bf16(v0[0], v0[1]); w.y = cvt_pk_bf16(v0[2], v0[3]); w.z = cvt_pk_bf16(v1[0], v1[1]); w.w = cvt_pk_bf16(v1[2], v1[3]);
;                     if (kv) {
;                         const int cseg = (u.pn & 1) * 256 + bj * HALF + wc * 32 + 8 * fq; const unsigned hd = (unsigned)cseg >> 6, dl = ((unsigned)cseg & 63u) >> 3;
;                         const unsigned pos = (unsigned)row & 4095u, key = pos & 63u; const unsigned rb = ((unsigned)row >> 12) * 2097152u + hd * 262144u + (pos >> 6) * 4096u;
;                         if (u.pn < 8) *(u32x4*)(Kb + rb + dl * 512u + key * 8u) = w;
;                         else *(u32x4*)(Vb + rb + (dl >> 2) * 2048u + (key >> 4) * 512u + (key & 15u) * 32u + (dl & 3u) * 8u) = w;
;                     } else *(u32x4*)(rowp + bj * HALF) = w; } }
.LBB0_356:
	s_and_b64 vcc, exec, s[8:9]
	s_nop 0
	v_mov_b32_e32 v136, v8
	v_mov_b32_e32 v137, v9
	v_mov_b32_e32 v170, v10
	v_mov_b32_e32 v171, v11
	v_mov_b32_e32 v138, v0
	v_mov_b32_e32 v139, v1
	v_mov_b32_e32 v172, v2
	v_mov_b32_e32 v173, v3
	s_cbranch_vccnz .LBB0_358
	s_nop 0
	v_pk_mul_f32 v[136:137], v[0:1], v[100:101]
	v_mul_f32_e32 v174, v10, v102
	v_pk_fma_f32 v[136:137], v[8:9], v[96:97], v[136:137] neg_lo:[0,0,1] neg_hi:[0,0,1]
	v_pk_mul_f32 v[96:97], v[0:1], v[96:97]
	v_mov_b32_e32 v186, v11
	v_pk_fma_f32 v[96:97], v[8:9], v[100:101], v[96:97]
	v_mul_f32_e32 v100, v2, v102
	v_mov_b32_e32 v187, v3
	v_mov_b32_e32 v102, v99
	v_pk_mul_f32 v[170:171], v[186:187], v[102:103]
	v_pk_mul_f32 v[138:139], v[166:167], v[96:97] op_sel_hi:[0,1]
	v_mul_f32_e32 v96, v10, v98
	v_mov_b32_e32 v97, v170
	v_mov_b32_e32 v101, v171
	v_mul_f32_e32 v172, v2, v98
	v_pk_add_f32 v[96:97], v[96:97], v[100:101] neg_lo:[0,1] neg_hi:[0,1]
	v_mov_b32_e32 v98, v103
	v_pk_mul_f32 v[170:171], v[166:167], v[96:97] op_sel_hi:[0,1]
	v_pk_mul_f32 v[96:97], v[186:187], v[98:99]
	v_pk_mul_f32 v[136:137], v[166:167], v[136:137] op_sel_hi:[0,1]
	v_mov_b32_e32 v175, v96
	v_mov_b32_e32 v173, v97
	v_pk_add_f32 v[96:97], v[174:175], v[172:173]
	s_nop 0
	v_pk_mul_f32 v[172:173], v[166:167], v[96:97] op_sel_hi:[0,1]
.LBB0_358:
	s_and_b64 vcc, exec, s[6:7]
	s_mov_b64 s[6:7], -1
	s_nop 0
	v_cvt_pk_bf16_f32 v128, v136, v137
	v_cvt_pk_bf16_f32 v129, v170, v171
	v_cvt_pk_bf16_f32 v130, v138, v139
	v_cvt_pk_bf16_f32 v131, v172, v173
	s_cbranch_vccnz .LBB0_360
	s_mov_b64 s[6:7], 0
	global_store_dwordx4 v[168:169], v[128:131], off offset:256
.LBB0_360:
	s_andn2_b64 vcc, exec, s[6:7]
	s_cbranch_vccnz .LBB0_365
	s_and_b32 s6, s39, 0x100
	s_nop 0
	v_add_lshl_u32 v132, s6, v179, 12
	v_and_b32_e32 v132, 0xfffc0000, v132
	v_add_u32_e32 v148, v185, v132
	s_and_b64 vcc, exec, s[4:5]
	s_mov_b64 s[4:5], -1
	s_cbranch_vccnz .LBB0_363
	v_lshl_add_u64 v[132:133], v[148:149], 1, v[152:153]
	s_mov_b64 s[4:5], 0
	global_store_dwordx4 v[132:133], v[128:131], off offset:3072

.LBB0_3761:
	s_add_i32 s0, s51, 3
	s_sub_i32 s1, s0, s48
	s_min_u32 s2, s0, s1
	s_lshl_b64 s[0:1], s[2:3], 13
	s_waitcnt lgkmcnt(0)
	s_barrier
	s_waitcnt vmcnt(3)
	ds_write_b128 v199, v[124:127] offset:16384
	s_waitcnt vmcnt(2)
	ds_write_b128 v199, v[128:131] offset:24576
	v_lshl_add_u64 v[6:7], v[180:181], 0, s[0:1]
	v_lshl_add_u64 v[8:9], v[182:183], 0, s[0:1]
	global_load_dwordx4 v[124:127], v[6:7], off
	global_load_dwordx4 v[128:131], v[8:9], off
	s_cmp_gt_u32 s51, s47
	s_cbranch_scc1 .LBB0_3765
	ds_read_b128 v[6:9], v200
	ds_read_b128 v[10:13], v200 offset:512
	v_lshrrev_b32_e32 v1, v160, v152
	v_lshrrev_b32_e32 v14, v160, v153
	v_bitop3_b32 v228, v1, s27, v1 bitop3:0xc
	v_bitop3_b32 v229, v1, s28, v1 bitop3:0xc
	v_bitop3_b32 v230, v1, s29, v1 bitop3:0xc
	v_bitop3_b32 v231, v1, s30, v1 bitop3:0xc
	s_waitcnt lgkmcnt(1)
	v_mfma_f32_32x32x16_bf16 v[80:95], v[6:9], v[144:147], v[64:79]
	v_mul_u32_u24_e32 v228, 0xf000, v228
	v_mul_u32_u24_e32 v229, 0x7800, v229
	v_mul_u32_u24_e32 v230, 0x3c00, v230
	v_mul_u32_u24_e32 v231, 0x1e00, v231
	s_waitcnt lgkmcnt(0)
	v_mfma_f32_32x32x16_bf16 v[96:111], v[10:13], v[144:147], v[64:79]
	ds_read_b128 v[6:9], v200 offset:2048
	ds_read_b128 v[10:13], v200 offset:2560
	v_bitop3_b32 v232, v14, s27, v14 bitop3:0xc
	v_bitop3_b32 v233, v14, s28, v14 bitop3:0xc
	v_bitop3_b32 v234, v14, s29, v14 bitop3:0xc
	v_bitop3_b32 v235, v14, s30, v14 bitop3:0xc
	v_mul_u32_u24_e32 v232, 0xf000, v232
	v_mul_u32_u24_e32 v233, 0x7800, v233
	v_mul_u32_u24_e32 v234, 0x3c00, v234
	v_mul_u32_u24_e32 v235, 0x1e00, v235
	s_waitcnt lgkmcnt(1)
	v_mfma_f32_32x32x16_bf16 v[80:95], v[6:9], v[136:139], v[80:95]
	v_bitop3_b32 v236, v1, s31, v1 bitop3:0xc
	v_bitop3_b32 v237, v1, s33, v1 bitop3:0xc
	v_bitop3_b32 v238, v1, s34, v1 bitop3:0xc
	v_bitop3_b32 v239, v1, s35, v1 bitop3:0xc
	s_waitcnt lgkmcnt(0)
	v_mfma_f32_32x32x16_bf16 v[96:111], v[10:13], v[136:139], v[96:111]
	ds_read_b128 v[6:9], v200 offset:4096
	ds_read_b128 v[10:13], v200 offset:4608
	v_mul_u32_u24_e32 v236, 0xf00, v236
	v_mul_u32_u24_e32 v237, 0x780, v237
	v_mul_u32_u24_e32 v238, 0x3c0, v238
	v_mul_u32_u24_e32 v239, 0x1e0, v239
	v_bitop3_b32 v224, v14, s31, v14 bitop3:0xc
	v_bitop3_b32 v225, v14, s33, v14 bitop3:0xc
	v_bitop3_b32 v226, v14, s34, v14 bitop3:0xc
	v_bitop3_b32 v227, v14, s35, v14 bitop3:0xc
	s_waitcnt lgkmcnt(1)
	v_mfma_f32_32x32x16_bf16 v[80:95], v[6:9], v[140:143], v[80:95]
	v_mul_u32_u24_e32 v224, 0xf00, v224
	v_mul_u32_u24_e32 v225, 0x780, v225
	v_mul_u32_u24_e32 v226, 0x3c0, v226
	v_mul_u32_u24_e32 v227, 0x1e0, v227
	s_waitcnt lgkmcnt(0)
	v_mfma_f32_32x32x16_bf16 v[96:111], v[10:13], v[140:143], v[96:111]
	ds_read_b128 v[6:9], v200 offset:6144
	ds_read_b128 v[10:13], v200 offset:6656
	s_xor_b64 s[4:5], s[20:21], -1
	s_waitcnt lgkmcnt(1)
	v_mfma_f32_32x32x16_bf16 v[80:95], v[6:9], v[148:151], v[80:95]
	s_waitcnt lgkmcnt(0)
	v_mfma_f32_32x32x16_bf16 v[96:111], v[10:13], v[148:151], v[96:111]
	v_mfma_f32_32x32x16_bf16 v[80:95], v[112:115], v[228:231], v[80:95]
	v_mfma_f32_32x32x16_bf16 v[96:111], v[112:115], v[232:235], v[96:111]
	v_mfma_f32_32x32x16_bf16 v[80:95], v[116:119], v[236:239], v[80:95]
	v_mfma_f32_32x32x16_bf16 v[96:111], v[116:119], v[224:227], v[96:111]
	s_nop 15
	s_nop 7
	v_max3_f32 v1, v80, v81, v82
	v_max3_f32 v6, v83, v84, v85
	v_max3_f32 v1, v1, v86, v87
	v_max3_f32 v6, v6, v88, v89
	v_max3_f32 v1, v1, v90, v91
	v_max3_f32 v6, v6, v92, v93
	v_max3_f32 v1, v1, v94, v95
	v_max_f32 v1, v1, v6
	s_nop 0
	v_max3_f32 v7, v96, v97, v98
	v_max3_f32 v6, v99, v100, v101
	v_max3_f32 v7, v7, v102, v103
	v_max3_f32 v6, v6, v104, v105
	v_max3_f32 v7, v7, v106, v107
	v_max3_f32 v6, v6, v108, v109
	v_max3_f32 v7, v7, v110, v111
	v_max3_f32 v7, v7, v6, v1
	s_nop 0
	v_mov_b32_e32 v1, v7
	s_nop 1
	v_permlane32_swap_b32_e32 v7, v1
	v_max_f32_e32 v1, v1, v1
	v_max_f32_e32 v6, v7, v7
	v_max_f32_e32 v1, v6, v1
	v_cmp_lt_f32_e64 s[0:1], s36, v1
	s_and_b64 s[10:11], s[0:1], s[4:5]
	v_cmp_lt_f32_e32 vcc, s37, v1
	s_or_b64 s[4:5], vcc, s[10:11]
	v_cndmask_b32_e64 v6, 0, 1, s[4:5]
	v_cmp_ne_u32_e32 vcc, 0, v6
	s_cbranch_vccz .LBB0_3764
	v_cndmask_b32_e64 v6, 0, v1, s[4:5]
	v_exp_f32_e64 v1, -v6
	v_add_f32_e32 v171, v171, v6
	s_or_b64 s[0:1], s[20:21], s[0:1]
	v_xor_b32_e32 v64, 0x80000000, v171
	v_cndmask_b32_e64 v8, v1, 1.0, s[10:11]
	s_andn2_b64 s[4:5], s[20:21], exec
	s_and_b64 s[0:1], s[0:1], exec
	v_pk_add_f32 v[80:81], v[80:81], v[6:7] op_sel_hi:[1,0] neg_lo:[0,1] neg_hi:[0,1]
	v_pk_add_f32 v[96:97], v[96:97], v[6:7] op_sel_hi:[1,0] neg_lo:[0,1] neg_hi:[0,1]
	v_pk_add_f32 v[82:83], v[82:83], v[6:7] op_sel_hi:[1,0] neg_lo:[0,1] neg_hi:[0,1]
	v_pk_add_f32 v[98:99], v[98:99], v[6:7] op_sel_hi:[1,0] neg_lo:[0,1] neg_hi:[0,1]
	v_pk_add_f32 v[84:85], v[84:85], v[6:7] op_sel_hi:[1,0] neg_lo:[0,1] neg_hi:[0,1]
	v_pk_add_f32 v[100:101], v[100:101], v[6:7] op_sel_hi:[1,0] neg_lo:[0,1] neg_hi:[0,1]
	v_pk_add_f32 v[86:87], v[86:87], v[6:7] op_sel_hi:[1,0] neg_lo:[0,1] neg_hi:[0,1]
	v_pk_add_f32 v[102:103], v[102:103], v[6:7] op_sel_hi:[1,0] neg_lo:[0,1] neg_hi:[0,1]
	v_pk_add_f32 v[88:89], v[88:89], v[6:7] op_sel_hi:[1,0] neg_lo:[0,1] neg_hi:[0,1]
	v_pk_add_f32 v[104:105], v[104:105], v[6:7] op_sel_hi:[1,0] neg_lo:[0,1] neg_hi:[0,1]
	v_pk_add_f32 v[90:91], v[90:91], v[6:7] op_sel_hi:[1,0] neg_lo:[0,1] neg_hi:[0,1]
	v_pk_add_f32 v[106:107], v[106:107], v[6:7] op_sel_hi:[1,0] neg_lo:[0,1] neg_hi:[0,1]
	v_pk_add_f32 v[92:93], v[92:93], v[6:7] op_sel_hi:[1,0] neg_lo:[0,1] neg_hi:[0,1]
	v_pk_add_f32 v[108:109], v[108:109], v[6:7] op_sel_hi:[1,0] neg_lo:[0,1] neg_hi:[0,1]
	v_pk_add_f32 v[94:95], v[94:95], v[6:7] op_sel_hi:[1,0] neg_lo:[0,1] neg_hi:[0,1]
	v_pk_add_f32 v[110:111], v[110:111], v[6:7] op_sel_hi:[1,0] neg_lo:[0,1] neg_hi:[0,1]
	v_mov_b32_e32 v65, v64
	v_mov_b32_e32 v66, v64
	v_mov_b32_e32 v67, v64
	v_mov_b32_e32 v68, v64
	v_mov_b32_e32 v69, v64
	v_mov_b32_e32 v70, v64
	v_mov_b32_e32 v71, v64
	v_mov_b32_e32 v72, v64
	v_mov_b32_e32 v73, v64
	v_mov_b32_e32 v74, v64
	v_mov_b32_e32 v75, v64
	v_mov_b32_e32 v76, v64
	v_mov_b32_e32 v77, v64
	v_mov_b32_e32 v78, v64
	v_mov_b32_e32 v79, v64
	v_pk_mul_f32 v[30:31], v[30:31], v[8:9] op_sel_hi:[1,0]
	v_pk_mul_f32 v[28:29], v[28:29], v[8:9] op_sel_hi:[1,0]
	v_pk_mul_f32 v[26:27], v[26:27], v[8:9] op_sel_hi:[1,0]
	v_pk_mul_f32 v[24:25], v[24:25], v[8:9] op_sel_hi:[1,0]
	v_pk_mul_f32 v[22:23], v[22:23], v[8:9] op_sel_hi:[1,0]
	v_pk_mul_f32 v[20:21], v[20:21], v[8:9] op_sel_hi:[1,0]
	v_pk_mul_f32 v[18:19], v[18:19], v[8:9] op_sel_hi:[1,0]
	v_pk_mul_f32 v[16:17], v[16:17], v[8:9] op_sel_hi:[1,0]
	v_pk_mul_f32 v[46:47], v[46:47], v[8:9] op_sel_hi:[1,0]
	v_pk_mul_f32 v[44:45], v[44:45], v[8:9] op_sel_hi:[1,0]
	v_pk_mul_f32 v[42:43], v[42:43], v[8:9] op_sel_hi:[1,0]
	v_pk_mul_f32 v[40:41], v[40:41], v[8:9] op_sel_hi:[1,0]
	v_pk_mul_f32 v[38:39], v[38:39], v[8:9] op_sel_hi:[1,0]
	v_pk_mul_f32 v[36:37], v[36:37], v[8:9] op_sel_hi:[1,0]
	v_pk_mul_f32 v[34:35], v[34:35], v[8:9] op_sel_hi:[1,0]
	v_pk_mul_f32 v[32:33], v[32:33], v[8:9] op_sel_hi:[1,0]
	v_pk_mul_f32 v[62:63], v[62:63], v[8:9] op_sel_hi:[1,0]
	v_pk_mul_f32 v[60:61], v[60:61], v[8:9] op_sel_hi:[1,0]
	v_pk_mul_f32 v[58:59], v[58:59], v[8:9] op_sel_hi:[1,0]
	v_pk_mul_f32 v[56:57], v[56:57], v[8:9] op_sel_hi:[1,0]
	v_pk_mul_f32 v[54:55], v[54:55], v[8:9] op_sel_hi:[1,0]
	v_pk_mul_f32 v[52:53], v[52:53], v[8:9] op_sel_hi:[1,0]
	v_pk_mul_f32 v[50:51], v[50:51], v[8:9] op_sel_hi:[1,0]
	v_pk_mul_f32 v[48:49], v[48:49], v[8:9] op_sel_hi:[1,0]
	s_or_b64 s[20:21], s[4:5], s[0:1]
.LBB0_3764:
	v_add_u32_e32 v1, 0, v157
	ds_read_b64_tr_b16 v[202:203], v1 offset:8192
	ds_read_b64_tr_b16 v[204:205], v1 offset:8704
	ds_read_b64_tr_b16 v[206:207], v1 offset:12288
	ds_read_b64_tr_b16 v[208:209], v1 offset:12800
	s_mov_b32 s9, s8
	v_mov_b64_e32 v[224:225], s[8:9]
	v_mov_b64_e32 v[226:227], s[8:9]
	v_exp_f32_e32 v80, v80
	v_exp_f32_e32 v81, v81
	v_exp_f32_e32 v82, v82
	v_exp_f32_e32 v83, v83
	v_exp_f32_e32 v84, v84
	v_exp_f32_e32 v85, v85
	v_exp_f32_e32 v86, v86
	v_exp_f32_e32 v87, v87
	v_cvt_pk_bf16_f32 v6, v80, v81
	v_cvt_pk_bf16_f32 v7, v82, v83
	v_cvt_pk_bf16_f32 v8, v84, v85
	v_cvt_pk_bf16_f32 v9, v86, v87
	ds_read_b64_tr_b16 v[210:211], v1 offset:9216
	ds_read_b64_tr_b16 v[212:213], v1 offset:9728
	ds_read_b64_tr_b16 v[214:215], v1 offset:13312
	ds_read_b64_tr_b16 v[216:217], v1 offset:13824
	s_waitcnt lgkmcnt(4)
	v_mfma_f32_32x32x16_bf16 v[16:31], v[202:205], v[6:9], v[16:31]
	v_exp_f32_e32 v88, v88
	v_exp_f32_e32 v89, v89
	v_exp_f32_e32 v90, v90
	v_mfma_f32_32x32x16_bf16 v[32:47], v[206:209], v[6:9], v[32:47]
	v_exp_f32_e32 v91, v91
	v_exp_f32_e32 v92, v92
	v_exp_f32_e32 v93, v93
	v_mfma_f32_32x32x16_bf16 v[48:63], v[224:227], v[6:9], v[48:63]
	v_exp_f32_e32 v94, v94
	v_exp_f32_e32 v95, v95
	v_cvt_pk_bf16_f32 v10, v88, v89
	v_cvt_pk_bf16_f32 v11, v90, v91
	v_cvt_pk_bf16_f32 v12, v92, v93
	v_cvt_pk_bf16_f32 v13, v94, v95
	ds_read_b64_tr_b16 v[202:203], v1 offset:10240
	ds_read_b64_tr_b16 v[204:205], v1 offset:10752
	ds_read_b64_tr_b16 v[206:207], v1 offset:14336
	ds_read_b64_tr_b16 v[208:209], v1 offset:14848
	s_waitcnt lgkmcnt(4)
	v_mfma_f32_32x32x16_bf16 v[16:31], v[210:213], v[10:13], v[16:31]
	v_exp_f32_e32 v96, v96
	v_exp_f32_e32 v97, v97
	v_exp_f32_e32 v98, v98
	v_mfma_f32_32x32x16_bf16 v[32:47], v[214:217], v[10:13], v[32:47]
	v_exp_f32_e32 v99, v99
	v_exp_f32_e32 v100, v100
	v_exp_f32_e32 v101, v101
	v_mfma_f32_32x32x16_bf16 v[48:63], v[224:227], v[10:13], v[48:63]
	v_exp_f32_e32 v102, v102
	v_exp_f32_e32 v103, v103
	v_cvt_pk_bf16_f32 v228, v96, v97
	v_cvt_pk_bf16_f32 v229, v98, v99
	v_cvt_pk_bf16_f32 v230, v100, v101
	v_cvt_pk_bf16_f32 v231, v102, v103
	ds_read_b64_tr_b16 v[210:211], v1 offset:11264
	ds_read_b64_tr_b16 v[212:213], v1 offset:11776
	ds_read_b64_tr_b16 v[214:215], v1 offset:15360
	ds_read_b64_tr_b16 v[216:217], v1 offset:15872
	s_waitcnt lgkmcnt(4)
	v_mfma_f32_32x32x16_bf16 v[16:31], v[202:205], v[228:231], v[16:31]
	v_exp_f32_e32 v104, v104
	v_exp_f32_e32 v105, v105
	v_exp_f32_e32 v106, v106
	v_mfma_f32_32x32x16_bf16 v[32:47], v[206:209], v[228:231], v[32:47]
	v_exp_f32_e32 v107, v107
	v_exp_f32_e32 v108, v108
	v_exp_f32_e32 v109, v109
	v_mfma_f32_32x32x16_bf16 v[48:63], v[224:227], v[228:231], v[48:63]
	v_exp_f32_e32 v110, v110
	v_exp_f32_e32 v111, v111
	v_cvt_pk_bf16_f32 v232, v104, v105
	v_cvt_pk_bf16_f32 v233, v106, v107
	v_cvt_pk_bf16_f32 v234, v108, v109
	v_cvt_pk_bf16_f32 v235, v110, v111
	s_waitcnt lgkmcnt(0)
	s_nop 0
	v_mfma_f32_32x32x16_bf16 v[16:31], v[210:213], v[232:235], v[16:31]
	v_mfma_f32_32x32x16_bf16 v[32:47], v[214:217], v[232:235], v[32:47]
	v_mfma_f32_32x32x16_bf16 v[48:63], v[224:227], v[232:235], v[48:63]
.LBB0_3765:
	s_cmp_ge_u32 s51, s46
	s_cselect_b32 s0, s49, 4
	s_add_i32 s0, s0, s51
	s_ashr_i32 s1, s0, 31
	s_lshl_b64 s[0:1], s[0:1], 13
	s_waitcnt lgkmcnt(0)
	s_barrier
	s_waitcnt vmcnt(3)
	ds_write_b128 v199, v[120:123]
	s_waitcnt vmcnt(2)
	ds_write_b128 v199, v[132:135] offset:8192
	v_lshl_add_u64 v[6:7], v[180:181], 0, s[0:1]
	v_lshl_add_u64 v[8:9], v[182:183], 0, s[0:1]
	global_load_dwordx4 v[120:123], v[6:7], off
	global_load_dwordx4 v[132:135], v[8:9], off
	s_cmp_ge_u32 s51, s47
	s_cbranch_scc1 .LBB0_3770
	ds_read_b128 v[6:9], v200 offset:16384
	ds_read_b128 v[10:13], v200 offset:16896
	v_lshrrev_b32_e32 v1, v160, v154
	v_lshrrev_b32_e32 v14, v160, v155
	v_bitop3_b32 v228, v1, s27, v1 bitop3:0xc
	v_bitop3_b32 v229, v1, s28, v1 bitop3:0xc
	v_bitop3_b32 v230, v1, s29, v1 bitop3:0xc
	v_bitop3_b32 v231, v1, s30, v1 bitop3:0xc
	s_waitcnt lgkmcnt(1)
	v_mfma_f32_32x32x16_bf16 v[80:95], v[6:9], v[144:147], v[64:79]
	v_mul_u32_u24_e32 v228, 0xf000, v228
	v_mul_u32_u24_e32 v229, 0x7800, v229
	v_mul_u32_u24_e32 v230, 0x3c00, v230
	v_mul_u32_u24_e32 v231, 0x1e00, v231
	s_waitcnt lgkmcnt(0)
	v_mfma_f32_32x32x16_bf16 v[96:111], v[10:13], v[144:147], v[64:79]
	ds_read_b128 v[6:9], v200 offset:18432
	ds_read_b128 v[10:13], v200 offset:18944
	v_bitop3_b32 v232, v14, s27, v14 bitop3:0xc
	v_bitop3_b32 v233, v14, s28, v14 bitop3:0xc
	v_bitop3_b32 v234, v14, s29, v14 bitop3:0xc
	v_bitop3_b32 v235, v14, s30, v14 bitop3:0xc
	v_mul_u32_u24_e32 v232, 0xf000, v232
	v_mul_u32_u24_e32 v233, 0x7800, v233
	v_mul_u32_u24_e32 v234, 0x3c00, v234
	v_mul_u32_u24_e32 v235, 0x1e00, v235
	s_waitcnt lgkmcnt(1)
	v_mfma_f32_32x32x16_bf16 v[80:95], v[6:9], v[136:139], v[80:95]
	v_bitop3_b32 v236, v1, s31, v1 bitop3:0xc
	v_bitop3_b32 v237, v1, s33, v1 bitop3:0xc
	v_bitop3_b32 v238, v1, s34, v1 bitop3:0xc
	v_bitop3_b32 v239, v1, s35, v1 bitop3:0xc
	s_waitcnt lgkmcnt(0)
	v_mfma_f32_32x32x16_bf16 v[96:111], v[10:13], v[136:139], v[96:111]
	ds_read_b128 v[6:9], v200 offset:20480
	ds_read_b128 v[10:13], v200 offset:20992
	v_mul_u32_u24_e32 v236, 0xf00, v236
	v_mul_u32_u24_e32 v237, 0x780, v237
	v_mul_u32_u24_e32 v238, 0x3c0, v238
	v_mul_u32_u24_e32 v239, 0x1e0, v239
	v_bitop3_b32 v224, v14, s31, v14 bitop3:0xc
	v_bitop3_b32 v225, v14, s33, v14 bitop3:0xc
	v_bitop3_b32 v226, v14, s34, v14 bitop3:0xc
	v_bitop3_b32 v227, v14, s35, v14 bitop3:0xc
	s_waitcnt lgkmcnt(1)
	v_mfma_f32_32x32x16_bf16 v[80:95], v[6:9], v[140:143], v[80:95]
	v_mul_u32_u24_e32 v224, 0xf00, v224
	v_mul_u32_u24_e32 v225, 0x780, v225
	v_mul_u32_u24_e32 v226, 0x3c0, v226
	v_mul_u32_u24_e32 v227, 0x1e0, v227
	s_waitcnt lgkmcnt(0)
	v_mfma_f32_32x32x16_bf16 v[96:111], v[10:13], v[140:143], v[96:111]
	ds_read_b128 v[6:9], v200 offset:22528
	ds_read_b128 v[10:13], v200 offset:23040
	s_xor_b64 s[4:5], s[20:21], -1
	v_cndmask_b32_e64 v1, 0, 1, s[4:5]
	v_cmp_ne_u32_e32 vcc, 0, v1
	s_waitcnt lgkmcnt(1)
	v_mfma_f32_32x32x16_bf16 v[80:95], v[6:9], v[148:151], v[80:95]
	s_waitcnt lgkmcnt(0)
	v_mfma_f32_32x32x16_bf16 v[96:111], v[10:13], v[148:151], v[96:111]
	v_mfma_f32_32x32x16_bf16 v[80:95], v[112:115], v[228:231], v[80:95]
	v_mfma_f32_32x32x16_bf16 v[96:111], v[112:115], v[232:235], v[96:111]
	v_mfma_f32_32x32x16_bf16 v[80:95], v[116:119], v[236:239], v[80:95]
	v_mfma_f32_32x32x16_bf16 v[96:111], v[116:119], v[224:227], v[96:111]
	s_cbranch_vccz .LBB0_3769
	s_nop 15
	s_nop 7
	v_max3_f32 v1, v80, v81, v82
	v_max3_f32 v6, v83, v84, v85
	v_max3_f32 v1, v1, v86, v87
	v_max3_f32 v6, v6, v88, v89
	v_max3_f32 v1, v1, v90, v91
	v_max3_f32 v6, v6, v92, v93
	v_max3_f32 v1, v1, v94, v95
	v_max_f32 v1, v1, v6
	s_nop 0
	v_max3_f32 v7, v96, v97, v98
	v_max3_f32 v6, v99, v100, v101
	v_max3_f32 v7, v7, v102, v103
	v_max3_f32 v6, v6, v104, v105
	v_max3_f32 v7, v7, v106, v107
	v_max3_f32 v6, v6, v108, v109
	v_max3_f32 v7, v7, v110, v111
	v_max3_f32 v7, v7, v6, v1
	s_nop 0
	v_mov_b32_e32 v1, v7
	s_nop 1
	v_permlane32_swap_b32_e32 v7, v1
	v_max_f32_e32 v1, v1, v1
	v_max_f32_e32 v6, v7, v7
	v_max_f32_e32 v1, v6, v1
	v_cmp_lt_f32_e64 s[0:1], s36, v1
	s_and_b64 s[10:11], s[0:1], s[4:5]
	v_cmp_lt_f32_e32 vcc, s37, v1
	s_or_b64 s[4:5], vcc, s[10:11]
	v_cndmask_b32_e64 v6, 0, 1, s[4:5]
	v_cmp_ne_u32_e32 vcc, 0, v6
	s_cbranch_vccz .LBB0_3769
	v_cndmask_b32_e64 v1, 0, v1, s[4:5]
	v_exp_f32_e64 v6, -v1
	v_add_f32_e32 v171, v171, v1
	s_or_b64 s[0:1], s[20:21], s[0:1]
	v_xor_b32_e32 v64, 0x80000000, v171
	v_cndmask_b32_e64 v6, v6, 1.0, s[10:11]
	s_andn2_b64 s[4:5], s[20:21], exec
	s_and_b64 s[0:1], s[0:1], exec
	v_mov_b32_e32 v65, v64
	v_mov_b32_e32 v66, v64
	v_mov_b32_e32 v67, v64
	v_mov_b32_e32 v68, v64
	v_mov_b32_e32 v69, v64
	v_mov_b32_e32 v70, v64
	v_mov_b32_e32 v71, v64
	v_mov_b32_e32 v72, v64
	v_mov_b32_e32 v73, v64
	v_mov_b32_e32 v74, v64
	v_mov_b32_e32 v75, v64
	v_mov_b32_e32 v76, v64
	v_mov_b32_e32 v77, v64
	v_mov_b32_e32 v78, v64
	v_mov_b32_e32 v79, v64
	v_pk_mul_f32 v[30:31], v[30:31], v[6:7] op_sel_hi:[1,0]
	v_pk_mul_f32 v[28:29], v[28:29], v[6:7] op_sel_hi:[1,0]
	v_pk_mul_f32 v[26:27], v[26:27], v[6:7] op_sel_hi:[1,0]
	v_pk_mul_f32 v[24:25], v[24:25], v[6:7] op_sel_hi:[1,0]
	v_pk_mul_f32 v[22:23], v[22:23], v[6:7] op_sel_hi:[1,0]
	v_pk_mul_f32 v[20:21], v[20:21], v[6:7] op_sel_hi:[1,0]
	v_pk_mul_f32 v[18:19], v[18:19], v[6:7] op_sel_hi:[1,0]
	v_pk_mul_f32 v[16:17], v[16:17], v[6:7] op_sel_hi:[1,0]
	v_pk_mul_f32 v[46:47], v[46:47], v[6:7] op_sel_hi:[1,0]
	v_pk_mul_f32 v[44:45], v[44:45], v[6:7] op_sel_hi:[1,0]
	v_pk_mul_f32 v[42:43], v[42:43], v[6:7] op_sel_hi:[1,0]
	v_pk_mul_f32 v[40:41], v[40:41], v[6:7] op_sel_hi:[1,0]
	v_pk_mul_f32 v[38:39], v[38:39], v[6:7] op_sel_hi:[1,0]
	v_pk_mul_f32 v[36:37], v[36:37], v[6:7] op_sel_hi:[1,0]
	v_pk_mul_f32 v[34:35], v[34:35], v[6:7] op_sel_hi:[1,0]
	v_pk_mul_f32 v[32:33], v[32:33], v[6:7] op_sel_hi:[1,0]
	v_pk_mul_f32 v[62:63], v[62:63], v[6:7] op_sel_hi:[1,0]
	v_pk_mul_f32 v[60:61], v[60:61], v[6:7] op_sel_hi:[1,0]
	v_pk_mul_f32 v[58:59], v[58:59], v[6:7] op_sel_hi:[1,0]
	v_pk_mul_f32 v[56:57], v[56:57], v[6:7] op_sel_hi:[1,0]
	v_pk_mul_f32 v[54:55], v[54:55], v[6:7] op_sel_hi:[1,0]
	v_pk_mul_f32 v[52:53], v[52:53], v[6:7] op_sel_hi:[1,0]
	v_pk_mul_f32 v[50:51], v[50:51], v[6:7] op_sel_hi:[1,0]
	v_pk_mul_f32 v[48:49], v[48:49], v[6:7] op_sel_hi:[1,0]
	v_sub_f32_e32 v95, v95, v1
	v_sub_f32_e32 v94, v94, v1
	v_sub_f32_e32 v93, v93, v1
	v_sub_f32_e32 v92, v92, v1
	v_sub_f32_e32 v91, v91, v1
	v_sub_f32_e32 v90, v90, v1
	v_sub_f32_e32 v89, v89, v1
	v_sub_f32_e32 v88, v88, v1
	v_sub_f32_e32 v87, v87, v1
	v_sub_f32_e32 v86, v86, v1
	v_sub_f32_e32 v85, v85, v1
	v_sub_f32_e32 v84, v84, v1
	v_sub_f32_e32 v83, v83, v1
	v_sub_f32_e32 v82, v82, v1
	v_sub_f32_e32 v81, v81, v1
	v_sub_f32_e32 v80, v80, v1
	v_sub_f32_e32 v111, v111, v1
	v_sub_f32_e32 v110, v110, v1
	v_sub_f32_e32 v109, v109, v1
	v_sub_f32_e32 v108, v108, v1
	v_sub_f32_e32 v107, v107, v1
	v_sub_f32_e32 v106, v106, v1
	v_sub_f32_e32 v105, v105, v1
	v_sub_f32_e32 v104, v104, v1
	v_sub_f32_e32 v103, v103, v1
	v_sub_f32_e32 v102, v102, v1
	v_sub_f32_e32 v101, v101, v1
	v_sub_f32_e32 v100, v100, v1
	v_sub_f32_e32 v99, v99, v1
	v_sub_f32_e32 v98, v98, v1
	v_sub_f32_e32 v97, v97, v1
	v_sub_f32_e32 v96, v96, v1
	s_or_b64 s[20:21], s[4:5], s[0:1]
.LBB0_3769:
	s_nop 8
	v_add_u32_e32 v1, 0, v157
	ds_read_b64_tr_b16 v[202:203], v1 offset:24576
	ds_read_b64_tr_b16 v[204:205], v1 offset:25088
	ds_read_b64_tr_b16 v[206:207], v1 offset:28672
	ds_read_b64_tr_b16 v[208:209], v1 offset:29184
	s_mov_b32 s9, s8
	v_mov_b64_e32 v[224:225], s[8:9]
	v_mov_b64_e32 v[226:227], s[8:9]
	v_exp_f32_e32 v80, v80
	v_exp_f32_e32 v81, v81
	v_exp_f32_e32 v82, v82
	v_exp_f32_e32 v83, v83
	v_exp_f32_e32 v84, v84
	v_exp_f32_e32 v85, v85
	v_exp_f32_e32 v86, v86
	v_exp_f32_e32 v87, v87
	v_cvt_pk_bf16_f32 v6, v80, v81
	v_cvt_pk_bf16_f32 v7, v82, v83
	v_cvt_pk_bf16_f32 v8, v84, v85
	v_cvt_pk_bf16_f32 v9, v86, v87
	ds_read_b64_tr_b16 v[210:211], v1 offset:25600
	ds_read_b64_tr_b16 v[212:213], v1 offset:26112
	ds_read_b64_tr_b16 v[214:215], v1 offset:29696
	ds_read_b64_tr_b16 v[216:217], v1 offset:30208
	s_waitcnt lgkmcnt(4)
	v_mfma_f32_32x32x16_bf16 v[16:31], v[202:205], v[6:9], v[16:31]
	v_exp_f32_e32 v88, v88
	v_exp_f32_e32 v89, v89
	v_exp_f32_e32 v90, v90
	v_mfma_f32_32x32x16_bf16 v[32:47], v[206:209], v[6:9], v[32:47]
	v_exp_f32_e32 v91, v91
	v_exp_f32_e32 v92, v92
	v_exp_f32_e32 v93, v93
	v_mfma_f32_32x32x16_bf16 v[48:63], v[224:227], v[6:9], v[48:63]
	v_exp_f32_e32 v94, v94
	v_exp_f32_e32 v95, v95
	v_cvt_pk_bf16_f32 v10, v88, v89
	v_cvt_pk_bf16_f32 v11, v90, v91
	v_cvt_pk_bf16_f32 v12, v92, v93
	v_cvt_pk_bf16_f32 v13, v94, v95
	ds_read_b64_tr_b16 v[202:203], v1 offset:26624
	ds_read_b64_tr_b16 v[204:205], v1 offset:27136
	ds_read_b64_tr_b16 v[206:207], v1 offset:30720
	ds_read_b64_tr_b16 v[208:209], v1 offset:31232
	s_waitcnt lgkmcnt(4)
	v_mfma_f32_32x32x16_bf16 v[16:31], v[210:213], v[10:13], v[16:31]
	v_exp_f32_e32 v96, v96
	v_exp_f32_e32 v97, v97
	v_exp_f32_e32 v98, v98
	v_mfma_f32_32x32x16_bf16 v[32:47], v[214:217], v[10:13], v[32:47]
	v_exp_f32_e32 v99, v99
	v_exp_f32_e32 v100, v100
	v_exp_f32_e32 v101, v101
	v_mfma_f32_32x32x16_bf16 v[48:63], v[224:227], v[10:13], v[48:63]
	v_exp_f32_e32 v102, v102
	v_exp_f32_e32 v103, v103
	v_cvt_pk_bf16_f32 v228, v96, v97
	v_cvt_pk_bf16_f32 v229, v98, v99
	v_cvt_pk_bf16_f32 v230, v100, v101
	v_cvt_pk_bf16_f32 v231, v102, v103
	ds_read_b64_tr_b16 v[210:211], v1 offset:27648
	ds_read_b64_tr_b16 v[212:213], v1 offset:28160
	ds_read_b64_tr_b16 v[214:215], v1 offset:31744
	ds_read_b64_tr_b16 v[216:217], v1 offset:32256
	s_waitcnt lgkmcnt(4)
	v_mfma_f32_32x32x16_bf16 v[16:31], v[202:205], v[228:231], v[16:31]
	v_exp_f32_e32 v104, v104
	v_exp_f32_e32 v105, v105
	v_exp_f32_e32 v106, v106
	v_mfma_f32_32x32x16_bf16 v[32:47], v[206:209], v[228:231], v[32:47]
	v_exp_f32_e32 v107, v107
	v_exp_f32_e32 v108, v108
	v_exp_f32_e32 v109, v109
	v_mfma_f32_32x32x16_bf16 v[48:63], v[224:227], v[228:231], v[48:63]
	v_exp_f32_e32 v110, v110
	v_exp_f32_e32 v111, v111
	v_cvt_pk_bf16_f32 v232, v104, v105
	v_cvt_pk_bf16_f32 v233, v106, v107
	v_cvt_pk_bf16_f32 v234, v108, v109
	v_cvt_pk_bf16_f32 v235, v110, v111
	s_waitcnt lgkmcnt(0)
	s_nop 0
	v_mfma_f32_32x32x16_bf16 v[16:31], v[210:213], v[232:235], v[16:31]
	v_mfma_f32_32x32x16_bf16 v[32:47], v[214:217], v[232:235], v[32:47]
	v_mfma_f32_32x32x16_bf16 v[48:63], v[224:227], v[232:235], v[48:63]
